# scan: chunk barrier and next block's first operand reads moved ahead of the second-half o reduce and o-store code (fills the block-start LDS latency)
# baseline (speedup 1.0000x reference)
; #define SCAN_BAR() asm volatile("s_barrier" ::: "memory")
; __device__ __forceinline__ void scan_unit(const Ctx& C0, const float* scn, int T, int quarter, const float* S0, float* Sout, unsigned char* obase, int mode) {
;     ...
;         float S0x = 0.f, S1x = 0.f, S2x = 0.f, S3x = 0.f;
;         if (S0) { const f32x4 t = *(const f32x4*)(S0 + irow * 64 + 4 * q); S0x = t.x; S1x = t.y; S2x = t.z; S3x = t.w; }
;         SCAN_BAR();
;         for (int k = 0; k < nch; ++k) {
;             const unsigned aq = (unsigned)(size_t)(C.lds + (k & 1) * SLOT_B) + 16u * (unsigned)q, av = (unsigned)(size_t)(C.lds + (k & 1) * SLOT_B) + (320u + (unsigned)irow) * 4u;
;             float osel0, osel1;
;             asm volatile(SCAN_CHUNK_ASM : "+v"(S0x), "+v"(S1x), "+v"(S2x), "+v"(S3x), "=&v"(osel0), "=&v"(osel1) : "v"(aq), "v"(av), "v"(q) : SCAN_CHUNK_CLOBBERS, "memory");
.LBB0_683:
	s_and_b64 vcc, exec, s[0:1]
	s_cbranch_vccz .LBB0_687
	v_lshrrev_b32_e32 v2, 4, v53
	s_lshl_b32 s1, s9, 2
	s_bfe_u32 s0, s72, 0x20003
	v_and_or_b32 v0, s1, 12, v2
	v_lshl_or_b32 v0, s0, 4, v0
	s_lshl_b32 s10, s2, 8
	s_lshl_b32 s0, s0, 6
	s_mul_i32 s9, s3, 0x5600000
	v_mov_b32_e32 v5, 0x500
	s_or_b32 s0, s10, s0
	s_mul_hi_i32 s1, s3, 0x5600000
	v_lshl_or_b32 v6, v0, 2, v5
	s_add_i32 s11, 0, 0xc000
	s_or_b32 s0, s9, s0
	s_waitcnt lgkmcnt(0)
	v_and_b32_e32 v3, 15, v52
	v_add_u32_e32 v9, 0, v6
	v_add_u32_e32 v11, s11, v6
	v_mov_b32_e32 v6, s0
	v_mov_b32_e32 v7, s1
	s_movk_i32 s0, 0x2b00
	v_mad_u64_u32 v[6:7], s[0:1], v3, s0, v[6:7]
	s_lshr_b32 s0, s8, 2
	s_and_b32 s0, s0, 48
	v_lshlrev_b32_e32 v2, 2, v2
	s_barrier
	v_or3_b32 v6, s0, v2, v6
	v_readlane_b32 s0, v253, 4
	v_lshlrev_b32_e32 v4, 4, v3
	v_readlane_b32 s1, v253, 5
	v_add_u32_e32 v5, 0, v4
	v_add_u32_e32 v10, s11, v4
	v_lshl_add_u64 v[6:7], s[0:1], 0, v[6:7]
	v_mov_b32_e32 v8, 0
	s_mov_b64 s[0:1], 0
	v_mov_b32_e32 v12, 0
	v_mov_b32_e32 v13, 0
	v_mov_b32_e32 v2, 0
	v_mov_b32_e32 v138, v2
	v_mov_b32_e32 v139, v13
	v_mov_b32_e32 v140, v12
	v_mov_b32_e32 v141, v8
	ds_read_b128 v[164:167], v5 offset:0
	ds_read_b128 v[168:171], v5 offset:256
	ds_read_b128 v[172:175], v5 offset:512
	ds_read_b128 v[176:179], v5 offset:768
	ds_read_b128 v[180:183], v5 offset:1024
	ds_read_b32 v184, v9 offset:0
	ds_read_b128 v[186:189], v5 offset:1536
	ds_read_b128 v[190:193], v5 offset:1792
	ds_read_b128 v[194:197], v5 offset:2048
	ds_read_b128 v[198:201], v5 offset:2304
	ds_read_b128 v[202:205], v5 offset:2560
	ds_read_b32 v206, v9 offset:1536
	ds_read_b128 v[208:211], v5 offset:3072
.LBB0_685:
	s_waitcnt lgkmcnt(12)
	v_pk_mul_f32 v[144:145], v[138:139], v[164:165]
	v_pk_fma_f32 v[144:145], v[140:141], v[166:167], v[144:145]
	v_add_f32 v146, v144, v145
	ds_read_b128 v[212:215], v5 offset:3328
	ds_read_b128 v[216:219], v5 offset:3584
	ds_read_b128 v[220:223], v5 offset:3840
	ds_read_b128 v[224:227], v5 offset:4096
	ds_read_b32 v228, v9 offset:3072
	ds_read_b128 v[230:233], v5 offset:4608
	v_add_f32_dpp v146, v146, v146 quad_perm:[1,0,3,2] row_mask:0xf bank_mask:0xf bound_ctrl:1
	s_nop 0
	s_nop 0
	v_add_f32_dpp v146, v146, v146 quad_perm:[2,3,0,1] row_mask:0xf bank_mask:0xf bound_ctrl:1
	s_waitcnt lgkmcnt(12)
	v_pk_mul_f32 v[176:177], v[176:177], v[184:185] op_sel_hi:[1,0]
	v_add_f32_dpp v146, v146, v146 row_half_mirror row_mask:0xf bank_mask:0xf bound_ctrl:1
	v_pk_mul_f32 v[178:179], v[178:179], v[184:185] op_sel_hi:[1,0]
	s_nop 0
	v_add_f32_dpp v146, v146, v146 row_mirror row_mask:0xf bank_mask:0xf bound_ctrl:1
	v_pk_fma_f32 v[176:177], v[146:147], v[168:169], v[176:177] op_sel_hi:[0,1,1] neg_lo:[1,0,0] neg_hi:[1,0,0]
	v_pk_fma_f32 v[178:179], v[146:147], v[170:171], v[178:179] op_sel_hi:[0,1,1] neg_lo:[1,0,0] neg_hi:[1,0,0]
	v_pk_fma_f32 v[138:139], v[138:139], v[172:173], v[176:177]
	v_pk_fma_f32 v[140:141], v[140:141], v[174:175], v[178:179]
	v_pk_mul_f32 v[144:145], v[138:139], v[186:187]
	v_pk_fma_f32 v[144:145], v[140:141], v[188:189], v[144:145]
	v_add_f32 v146, v144, v145
	ds_read_b128 v[234:237], v5 offset:4864
	ds_read_b128 v[238:241], v5 offset:5120
	ds_read_b128 v[242:245], v5 offset:5376
	ds_read_b128 v[246:249], v5 offset:5632
	ds_read_b32 v250, v9 offset:4608
	ds_read_b128 v[164:167], v5 offset:6144
	v_add_f32_dpp v146, v146, v146 quad_perm:[1,0,3,2] row_mask:0xf bank_mask:0xf bound_ctrl:1
	v_pk_mul_f32 v[180:181], v[138:139], v[180:181]
	v_pk_fma_f32 v[180:181], v[140:141], v[182:183], v[180:181]
	v_add_f32_dpp v146, v146, v146 quad_perm:[2,3,0,1] row_mask:0xf bank_mask:0xf bound_ctrl:1
	s_waitcnt lgkmcnt(12)
	v_pk_mul_f32 v[198:199], v[198:199], v[206:207] op_sel_hi:[1,0]
	v_add_f32_dpp v146, v146, v146 row_half_mirror row_mask:0xf bank_mask:0xf bound_ctrl:1
	v_pk_mul_f32 v[200:201], v[200:201], v[206:207] op_sel_hi:[1,0]
	v_add_f32 v148, v180, v181
	v_add_f32_dpp v146, v146, v146 row_mirror row_mask:0xf bank_mask:0xf bound_ctrl:1
	v_pk_fma_f32 v[198:199], v[146:147], v[190:191], v[198:199] op_sel_hi:[0,1,1] neg_lo:[1,0,0] neg_hi:[1,0,0]
	v_pk_fma_f32 v[200:201], v[146:147], v[192:193], v[200:201] op_sel_hi:[0,1,1] neg_lo:[1,0,0] neg_hi:[1,0,0]
	v_pk_fma_f32 v[138:139], v[138:139], v[194:195], v[198:199]
	v_pk_fma_f32 v[140:141], v[140:141], v[196:197], v[200:201]
	v_pk_mul_f32 v[144:145], v[138:139], v[208:209]
	v_pk_fma_f32 v[144:145], v[140:141], v[210:211], v[144:145]
	v_add_f32 v146, v144, v145
	ds_read_b128 v[168:171], v5 offset:6400
	ds_read_b128 v[172:175], v5 offset:6656
	ds_read_b128 v[176:179], v5 offset:6912
	ds_read_b128 v[180:183], v5 offset:7168
	ds_read_b32 v184, v9 offset:6144
	ds_read_b128 v[186:189], v5 offset:7680
	v_add_f32_dpp v146, v146, v146 quad_perm:[1,0,3,2] row_mask:0xf bank_mask:0xf bound_ctrl:1
	v_pk_mul_f32 v[202:203], v[138:139], v[202:203]
	v_pk_fma_f32 v[202:203], v[140:141], v[204:205], v[202:203]
	v_add_f32_dpp v146, v146, v146 quad_perm:[2,3,0,1] row_mask:0xf bank_mask:0xf bound_ctrl:1
	s_waitcnt lgkmcnt(12)
	v_pk_mul_f32 v[220:221], v[220:221], v[228:229] op_sel_hi:[1,0]
	v_add_f32_dpp v146, v146, v146 row_half_mirror row_mask:0xf bank_mask:0xf bound_ctrl:1
	v_pk_mul_f32 v[222:223], v[222:223], v[228:229] op_sel_hi:[1,0]
	v_add_f32 v149, v202, v203
	v_add_f32_dpp v146, v146, v146 row_mirror row_mask:0xf bank_mask:0xf bound_ctrl:1
	v_pk_fma_f32 v[220:221], v[146:147], v[212:213], v[220:221] op_sel_hi:[0,1,1] neg_lo:[1,0,0] neg_hi:[1,0,0]
	v_pk_fma_f32 v[222:223], v[146:147], v[214:215], v[222:223] op_sel_hi:[0,1,1] neg_lo:[1,0,0] neg_hi:[1,0,0]
	v_pk_fma_f32 v[138:139], v[138:139], v[216:217], v[220:221]
	v_pk_fma_f32 v[140:141], v[140:141], v[218:219], v[222:223]
	v_pk_mul_f32 v[144:145], v[138:139], v[230:231]
	v_pk_fma_f32 v[144:145], v[140:141], v[232:233], v[144:145]
	v_add_f32 v146, v144, v145
	ds_read_b128 v[190:193], v5 offset:7936
	ds_read_b128 v[194:197], v5 offset:8192
	ds_read_b128 v[198:201], v5 offset:8448
	ds_read_b128 v[202:205], v5 offset:8704
	ds_read_b32 v206, v9 offset:7680
	ds_read_b128 v[208:211], v5 offset:9216
	v_add_f32_dpp v146, v146, v146 quad_perm:[1,0,3,2] row_mask:0xf bank_mask:0xf bound_ctrl:1
	v_pk_mul_f32 v[224:225], v[138:139], v[224:225]
	v_pk_fma_f32 v[224:225], v[140:141], v[226:227], v[224:225]
	v_add_f32_dpp v146, v146, v146 quad_perm:[2,3,0,1] row_mask:0xf bank_mask:0xf bound_ctrl:1
	s_waitcnt lgkmcnt(12)
	v_pk_mul_f32 v[242:243], v[242:243], v[250:251] op_sel_hi:[1,0]
	v_add_f32_dpp v146, v146, v146 row_half_mirror row_mask:0xf bank_mask:0xf bound_ctrl:1
	v_pk_mul_f32 v[244:245], v[244:245], v[250:251] op_sel_hi:[1,0]
	v_add_f32 v150, v224, v225
	v_add_f32_dpp v146, v146, v146 row_mirror row_mask:0xf bank_mask:0xf bound_ctrl:1
	v_pk_fma_f32 v[242:243], v[146:147], v[234:235], v[242:243] op_sel_hi:[0,1,1] neg_lo:[1,0,0] neg_hi:[1,0,0]
	v_pk_fma_f32 v[244:245], v[146:147], v[236:237], v[244:245] op_sel_hi:[0,1,1] neg_lo:[1,0,0] neg_hi:[1,0,0]
	v_pk_fma_f32 v[138:139], v[138:139], v[238:239], v[242:243]
	v_pk_fma_f32 v[140:141], v[140:141], v[240:241], v[244:245]
	v_pk_mul_f32 v[144:145], v[138:139], v[164:165]
	v_pk_fma_f32 v[144:145], v[140:141], v[166:167], v[144:145]
	v_add_f32 v146, v144, v145
	ds_read_b128 v[212:215], v5 offset:9472
	ds_read_b128 v[216:219], v5 offset:9728
	ds_read_b128 v[220:223], v5 offset:9984
	ds_read_b128 v[224:227], v5 offset:10240
	ds_read_b32 v228, v9 offset:9216
	ds_read_b128 v[230:233], v5 offset:10752
	v_add_f32_dpp v146, v146, v146 quad_perm:[1,0,3,2] row_mask:0xf bank_mask:0xf bound_ctrl:1
	v_pk_mul_f32 v[246:247], v[138:139], v[246:247]
	v_pk_fma_f32 v[246:247], v[140:141], v[248:249], v[246:247]
	v_add_f32_dpp v146, v146, v146 quad_perm:[2,3,0,1] row_mask:0xf bank_mask:0xf bound_ctrl:1
	s_waitcnt lgkmcnt(12)
	v_pk_mul_f32 v[176:177], v[176:177], v[184:185] op_sel_hi:[1,0]
	v_add_f32_dpp v146, v146, v146 row_half_mirror row_mask:0xf bank_mask:0xf bound_ctrl:1
	v_pk_mul_f32 v[178:179], v[178:179], v[184:185] op_sel_hi:[1,0]
	v_add_f32 v151, v246, v247
	v_add_f32_dpp v146, v146, v146 row_mirror row_mask:0xf bank_mask:0xf bound_ctrl:1
	v_pk_fma_f32 v[176:177], v[146:147], v[168:169], v[176:177] op_sel_hi:[0,1,1] neg_lo:[1,0,0] neg_hi:[1,0,0]
	v_pk_fma_f32 v[178:179], v[146:147], v[170:171], v[178:179] op_sel_hi:[0,1,1] neg_lo:[1,0,0] neg_hi:[1,0,0]
	v_pk_fma_f32 v[138:139], v[138:139], v[172:173], v[176:177]
	v_pk_fma_f32 v[140:141], v[140:141], v[174:175], v[178:179]
	v_pk_mul_f32 v[144:145], v[138:139], v[186:187]
	v_pk_fma_f32 v[144:145], v[140:141], v[188:189], v[144:145]
	v_add_f32 v146, v144, v145
	ds_read_b128 v[234:237], v5 offset:11008
	ds_read_b128 v[238:241], v5 offset:11264
	ds_read_b128 v[242:245], v5 offset:11520
	ds_read_b128 v[246:249], v5 offset:11776
	ds_read_b32 v250, v9 offset:10752
	ds_read_b128 v[164:167], v5 offset:12288
	v_add_f32_dpp v146, v146, v146 quad_perm:[1,0,3,2] row_mask:0xf bank_mask:0xf bound_ctrl:1
	v_pk_mul_f32 v[180:181], v[138:139], v[180:181]
	v_pk_fma_f32 v[180:181], v[140:141], v[182:183], v[180:181]
	v_add_f32_dpp v146, v146, v146 quad_perm:[2,3,0,1] row_mask:0xf bank_mask:0xf bound_ctrl:1
	s_waitcnt lgkmcnt(12)
	v_pk_mul_f32 v[198:199], v[198:199], v[206:207] op_sel_hi:[1,0]
	v_add_f32_dpp v146, v146, v146 row_half_mirror row_mask:0xf bank_mask:0xf bound_ctrl:1
	v_pk_mul_f32 v[200:201], v[200:201], v[206:207] op_sel_hi:[1,0]
	v_add_f32 v152, v180, v181
	v_add_f32_dpp v146, v146, v146 row_mirror row_mask:0xf bank_mask:0xf bound_ctrl:1
	v_pk_fma_f32 v[198:199], v[146:147], v[190:191], v[198:199] op_sel_hi:[0,1,1] neg_lo:[1,0,0] neg_hi:[1,0,0]
	v_pk_fma_f32 v[200:201], v[146:147], v[192:193], v[200:201] op_sel_hi:[0,1,1] neg_lo:[1,0,0] neg_hi:[1,0,0]
	v_pk_fma_f32 v[138:139], v[138:139], v[194:195], v[198:199]
	v_pk_fma_f32 v[140:141], v[140:141], v[196:197], v[200:201]
	v_pk_mul_f32 v[144:145], v[138:139], v[208:209]
	v_pk_fma_f32 v[144:145], v[140:141], v[210:211], v[144:145]
	v_add_f32 v146, v144, v145
	ds_read_b128 v[168:171], v5 offset:12544
	ds_read_b128 v[172:175], v5 offset:12800
	ds_read_b128 v[176:179], v5 offset:13056
	ds_read_b128 v[180:183], v5 offset:13312
	ds_read_b32 v184, v9 offset:12288
	ds_read_b128 v[186:189], v5 offset:13824
	v_add_f32_dpp v146, v146, v146 quad_perm:[1,0,3,2] row_mask:0xf bank_mask:0xf bound_ctrl:1
	v_pk_mul_f32 v[202:203], v[138:139], v[202:203]
	v_pk_fma_f32 v[202:203], v[140:141], v[204:205], v[202:203]
	v_add_f32_dpp v146, v146, v146 quad_perm:[2,3,0,1] row_mask:0xf bank_mask:0xf bound_ctrl:1
	s_waitcnt lgkmcnt(12)
	v_pk_mul_f32 v[220:221], v[220:221], v[228:229] op_sel_hi:[1,0]
	v_add_f32_dpp v146, v146, v146 row_half_mirror row_mask:0xf bank_mask:0xf bound_ctrl:1
	v_pk_mul_f32 v[222:223], v[222:223], v[228:229] op_sel_hi:[1,0]
	v_add_f32 v153, v202, v203
	v_add_f32_dpp v146, v146, v146 row_mirror row_mask:0xf bank_mask:0xf bound_ctrl:1
	v_pk_fma_f32 v[220:221], v[146:147], v[212:213], v[220:221] op_sel_hi:[0,1,1] neg_lo:[1,0,0] neg_hi:[1,0,0]
	v_pk_fma_f32 v[222:223], v[146:147], v[214:215], v[222:223] op_sel_hi:[0,1,1] neg_lo:[1,0,0] neg_hi:[1,0,0]
	v_pk_fma_f32 v[138:139], v[138:139], v[216:217], v[220:221]
	v_pk_fma_f32 v[140:141], v[140:141], v[218:219], v[222:223]
	v_pk_mul_f32 v[144:145], v[138:139], v[230:231]
	v_pk_fma_f32 v[144:145], v[140:141], v[232:233], v[144:145]
	v_add_f32 v146, v144, v145
	ds_read_b128 v[190:193], v5 offset:14080
	ds_read_b128 v[194:197], v5 offset:14336
	ds_read_b128 v[198:201], v5 offset:14592
	ds_read_b128 v[202:205], v5 offset:14848
	ds_read_b32 v206, v9 offset:13824
	ds_read_b128 v[208:211], v5 offset:15360
	v_add_f32_dpp v146, v146, v146 quad_perm:[1,0,3,2] row_mask:0xf bank_mask:0xf bound_ctrl:1
	v_pk_mul_f32 v[224:225], v[138:139], v[224:225]
	v_pk_fma_f32 v[224:225], v[140:141], v[226:227], v[224:225]
	v_add_f32_dpp v146, v146, v146 quad_perm:[2,3,0,1] row_mask:0xf bank_mask:0xf bound_ctrl:1
	s_waitcnt lgkmcnt(12)
	v_pk_mul_f32 v[242:243], v[242:243], v[250:251] op_sel_hi:[1,0]
	v_add_f32_dpp v146, v146, v146 row_half_mirror row_mask:0xf bank_mask:0xf bound_ctrl:1
	v_pk_mul_f32 v[244:245], v[244:245], v[250:251] op_sel_hi:[1,0]
	v_add_f32 v154, v224, v225
	v_add_f32_dpp v146, v146, v146 row_mirror row_mask:0xf bank_mask:0xf bound_ctrl:1
	v_pk_fma_f32 v[242:243], v[146:147], v[234:235], v[242:243] op_sel_hi:[0,1,1] neg_lo:[1,0,0] neg_hi:[1,0,0]
	v_pk_fma_f32 v[244:245], v[146:147], v[236:237], v[244:245] op_sel_hi:[0,1,1] neg_lo:[1,0,0] neg_hi:[1,0,0]
	v_pk_fma_f32 v[138:139], v[138:139], v[238:239], v[242:243]
	v_pk_fma_f32 v[140:141], v[140:141], v[240:241], v[244:245]
	v_pk_mul_f32 v[144:145], v[138:139], v[164:165]
	v_pk_fma_f32 v[144:145], v[140:141], v[166:167], v[144:145]
	v_add_f32 v146, v144, v145
	ds_read_b128 v[212:215], v5 offset:15616
	ds_read_b128 v[216:219], v5 offset:15872
	ds_read_b128 v[220:223], v5 offset:16128
	ds_read_b128 v[224:227], v5 offset:16384
	ds_read_b32 v228, v9 offset:15360
	ds_read_b128 v[230:233], v5 offset:16896
	v_add_f32_dpp v146, v146, v146 quad_perm:[1,0,3,2] row_mask:0xf bank_mask:0xf bound_ctrl:1
	v_pk_mul_f32 v[246:247], v[138:139], v[246:247]
	v_pk_fma_f32 v[246:247], v[140:141], v[248:249], v[246:247]
	v_add_f32_dpp v146, v146, v146 quad_perm:[2,3,0,1] row_mask:0xf bank_mask:0xf bound_ctrl:1
	s_waitcnt lgkmcnt(12)
	v_pk_mul_f32 v[176:177], v[176:177], v[184:185] op_sel_hi:[1,0]
	v_add_f32_dpp v146, v146, v146 row_half_mirror row_mask:0xf bank_mask:0xf bound_ctrl:1
	v_pk_mul_f32 v[178:179], v[178:179], v[184:185] op_sel_hi:[1,0]
	v_add_f32 v155, v246, v247
	v_add_f32_dpp v146, v146, v146 row_mirror row_mask:0xf bank_mask:0xf bound_ctrl:1
	v_pk_fma_f32 v[176:177], v[146:147], v[168:169], v[176:177] op_sel_hi:[0,1,1] neg_lo:[1,0,0] neg_hi:[1,0,0]
	v_pk_fma_f32 v[178:179], v[146:147], v[170:171], v[178:179] op_sel_hi:[0,1,1] neg_lo:[1,0,0] neg_hi:[1,0,0]
	v_pk_fma_f32 v[138:139], v[138:139], v[172:173], v[176:177]
	v_pk_fma_f32 v[140:141], v[140:141], v[174:175], v[178:179]
	v_pk_mul_f32 v[144:145], v[138:139], v[186:187]
	v_pk_fma_f32 v[144:145], v[140:141], v[188:189], v[144:145]
	v_add_f32 v146, v144, v145
	ds_read_b128 v[234:237], v5 offset:17152
	ds_read_b128 v[238:241], v5 offset:17408
	ds_read_b128 v[242:245], v5 offset:17664
	ds_read_b128 v[246:249], v5 offset:17920
	ds_read_b32 v250, v9 offset:16896
	ds_read_b128 v[164:167], v5 offset:18432
	v_add_f32_dpp v146, v146, v146 quad_perm:[1,0,3,2] row_mask:0xf bank_mask:0xf bound_ctrl:1
	v_pk_mul_f32 v[180:181], v[138:139], v[180:181]
	v_pk_fma_f32 v[180:181], v[140:141], v[182:183], v[180:181]
	v_add_f32_dpp v146, v146, v146 quad_perm:[2,3,0,1] row_mask:0xf bank_mask:0xf bound_ctrl:1
	s_waitcnt lgkmcnt(12)
	v_pk_mul_f32 v[198:199], v[198:199], v[206:207] op_sel_hi:[1,0]
	v_add_f32_dpp v146, v146, v146 row_half_mirror row_mask:0xf bank_mask:0xf bound_ctrl:1
	v_pk_mul_f32 v[200:201], v[200:201], v[206:207] op_sel_hi:[1,0]
	v_add_f32 v156, v180, v181
	v_add_f32_dpp v146, v146, v146 row_mirror row_mask:0xf bank_mask:0xf bound_ctrl:1
	v_pk_fma_f32 v[198:199], v[146:147], v[190:191], v[198:199] op_sel_hi:[0,1,1] neg_lo:[1,0,0] neg_hi:[1,0,0]
	v_pk_fma_f32 v[200:201], v[146:147], v[192:193], v[200:201] op_sel_hi:[0,1,1] neg_lo:[1,0,0] neg_hi:[1,0,0]
	v_pk_fma_f32 v[138:139], v[138:139], v[194:195], v[198:199]
	v_pk_fma_f32 v[140:141], v[140:141], v[196:197], v[200:201]
	v_pk_mul_f32 v[144:145], v[138:139], v[208:209]
	v_pk_fma_f32 v[144:145], v[140:141], v[210:211], v[144:145]
	v_add_f32 v146, v144, v145
	ds_read_b128 v[168:171], v5 offset:18688
	ds_read_b128 v[172:175], v5 offset:18944
	ds_read_b128 v[176:179], v5 offset:19200
	ds_read_b128 v[180:183], v5 offset:19456
	ds_read_b32 v184, v9 offset:18432
	ds_read_b128 v[186:189], v5 offset:19968
	v_add_f32_dpp v146, v146, v146 quad_perm:[1,0,3,2] row_mask:0xf bank_mask:0xf bound_ctrl:1
	v_pk_mul_f32 v[202:203], v[138:139], v[202:203]
	v_pk_fma_f32 v[202:203], v[140:141], v[204:205], v[202:203]
	v_add_f32_dpp v146, v146, v146 quad_perm:[2,3,0,1] row_mask:0xf bank_mask:0xf bound_ctrl:1
	s_waitcnt lgkmcnt(12)
	v_pk_mul_f32 v[220:221], v[220:221], v[228:229] op_sel_hi:[1,0]
	v_add_f32_dpp v146, v146, v146 row_half_mirror row_mask:0xf bank_mask:0xf bound_ctrl:1
	v_pk_mul_f32 v[222:223], v[222:223], v[228:229] op_sel_hi:[1,0]
	v_add_f32 v157, v202, v203
	v_add_f32_dpp v146, v146, v146 row_mirror row_mask:0xf bank_mask:0xf bound_ctrl:1
	v_pk_fma_f32 v[220:221], v[146:147], v[212:213], v[220:221] op_sel_hi:[0,1,1] neg_lo:[1,0,0] neg_hi:[1,0,0]
	v_pk_fma_f32 v[222:223], v[146:147], v[214:215], v[222:223] op_sel_hi:[0,1,1] neg_lo:[1,0,0] neg_hi:[1,0,0]
	v_pk_fma_f32 v[138:139], v[138:139], v[216:217], v[220:221]
	v_pk_fma_f32 v[140:141], v[140:141], v[218:219], v[222:223]
	v_pk_mul_f32 v[144:145], v[138:139], v[230:231]
	v_pk_fma_f32 v[144:145], v[140:141], v[232:233], v[144:145]
	v_add_f32 v146, v144, v145
	ds_read_b128 v[190:193], v5 offset:20224
	ds_read_b128 v[194:197], v5 offset:20480
	ds_read_b128 v[198:201], v5 offset:20736
	ds_read_b128 v[202:205], v5 offset:20992
	ds_read_b32 v206, v9 offset:19968
	ds_read_b128 v[208:211], v5 offset:21504
	v_add_f32_dpp v146, v146, v146 quad_perm:[1,0,3,2] row_mask:0xf bank_mask:0xf bound_ctrl:1
	v_pk_mul_f32 v[224:225], v[138:139], v[224:225]
	v_pk_fma_f32 v[224:225], v[140:141], v[226:227], v[224:225]
	v_add_f32_dpp v146, v146, v146 quad_perm:[2,3,0,1] row_mask:0xf bank_mask:0xf bound_ctrl:1
	s_waitcnt lgkmcnt(12)
	v_pk_mul_f32 v[242:243], v[242:243], v[250:251] op_sel_hi:[1,0]
	v_add_f32_dpp v146, v146, v146 row_half_mirror row_mask:0xf bank_mask:0xf bound_ctrl:1
	v_pk_mul_f32 v[244:245], v[244:245], v[250:251] op_sel_hi:[1,0]
	v_add_f32 v158, v224, v225
	v_add_f32_dpp v146, v146, v146 row_mirror row_mask:0xf bank_mask:0xf bound_ctrl:1
	v_pk_fma_f32 v[242:243], v[146:147], v[234:235], v[242:243] op_sel_hi:[0,1,1] neg_lo:[1,0,0] neg_hi:[1,0,0]
	v_pk_fma_f32 v[244:245], v[146:147], v[236:237], v[244:245] op_sel_hi:[0,1,1] neg_lo:[1,0,0] neg_hi:[1,0,0]
	v_pk_fma_f32 v[138:139], v[138:139], v[238:239], v[242:243]
	v_pk_fma_f32 v[140:141], v[140:141], v[240:241], v[244:245]
	v_pk_mul_f32 v[144:145], v[138:139], v[164:165]
	v_pk_fma_f32 v[144:145], v[140:141], v[166:167], v[144:145]
	v_add_f32 v146, v144, v145
	ds_read_b128 v[212:215], v5 offset:21760
	ds_read_b128 v[216:219], v5 offset:22016
	ds_read_b128 v[220:223], v5 offset:22272
	ds_read_b128 v[224:227], v5 offset:22528
	ds_read_b32 v228, v9 offset:21504
	ds_read_b128 v[230:233], v5 offset:23040
	v_add_f32_dpp v146, v146, v146 quad_perm:[1,0,3,2] row_mask:0xf bank_mask:0xf bound_ctrl:1
	v_pk_mul_f32 v[246:247], v[138:139], v[246:247]
	v_pk_fma_f32 v[246:247], v[140:141], v[248:249], v[246:247]
	v_add_f32_dpp v146, v146, v146 quad_perm:[2,3,0,1] row_mask:0xf bank_mask:0xf bound_ctrl:1
	s_waitcnt lgkmcnt(12)
	v_pk_mul_f32 v[176:177], v[176:177], v[184:185] op_sel_hi:[1,0]
	v_add_f32_dpp v146, v146, v146 row_half_mirror row_mask:0xf bank_mask:0xf bound_ctrl:1
	v_pk_mul_f32 v[178:179], v[178:179], v[184:185] op_sel_hi:[1,0]
	v_add_f32 v159, v246, v247
	v_add_f32_dpp v146, v146, v146 row_mirror row_mask:0xf bank_mask:0xf bound_ctrl:1
	v_pk_fma_f32 v[176:177], v[146:147], v[168:169], v[176:177] op_sel_hi:[0,1,1] neg_lo:[1,0,0] neg_hi:[1,0,0]
	v_pk_fma_f32 v[178:179], v[146:147], v[170:171], v[178:179] op_sel_hi:[0,1,1] neg_lo:[1,0,0] neg_hi:[1,0,0]
	v_pk_fma_f32 v[138:139], v[138:139], v[172:173], v[176:177]
	v_pk_fma_f32 v[140:141], v[140:141], v[174:175], v[178:179]
	v_pk_mul_f32 v[144:145], v[138:139], v[186:187]
	v_pk_fma_f32 v[144:145], v[140:141], v[188:189], v[144:145]
	v_add_f32 v146, v144, v145
	ds_read_b128 v[234:237], v5 offset:23296
	ds_read_b128 v[238:241], v5 offset:23552
	ds_read_b128 v[242:245], v5 offset:23808
	ds_read_b128 v[246:249], v5 offset:24064
	ds_read_b32 v250, v9 offset:23040
	ds_read_b128 v[164:167], v5 offset:24576
	v_add_f32_dpp v146, v146, v146 quad_perm:[1,0,3,2] row_mask:0xf bank_mask:0xf bound_ctrl:1
	v_pk_mul_f32 v[180:181], v[138:139], v[180:181]
	v_pk_fma_f32 v[180:181], v[140:141], v[182:183], v[180:181]
	v_add_f32_dpp v146, v146, v146 quad_perm:[2,3,0,1] row_mask:0xf bank_mask:0xf bound_ctrl:1
	s_waitcnt lgkmcnt(12)
	v_pk_mul_f32 v[198:199], v[198:199], v[206:207] op_sel_hi:[1,0]
	v_add_f32_dpp v146, v146, v146 row_half_mirror row_mask:0xf bank_mask:0xf bound_ctrl:1
	v_pk_mul_f32 v[200:201], v[200:201], v[206:207] op_sel_hi:[1,0]
	v_add_f32 v160, v180, v181
	v_add_f32_dpp v146, v146, v146 row_mirror row_mask:0xf bank_mask:0xf bound_ctrl:1
	v_pk_fma_f32 v[198:199], v[146:147], v[190:191], v[198:199] op_sel_hi:[0,1,1] neg_lo:[1,0,0] neg_hi:[1,0,0]
	v_pk_fma_f32 v[200:201], v[146:147], v[192:193], v[200:201] op_sel_hi:[0,1,1] neg_lo:[1,0,0] neg_hi:[1,0,0]
	v_pk_fma_f32 v[138:139], v[138:139], v[194:195], v[198:199]
	v_pk_fma_f32 v[140:141], v[140:141], v[196:197], v[200:201]
	v_pk_mul_f32 v[144:145], v[138:139], v[208:209]
	v_pk_fma_f32 v[144:145], v[140:141], v[210:211], v[144:145]
	v_add_f32 v146, v144, v145
	ds_read_b128 v[168:171], v5 offset:24832
	ds_read_b128 v[172:175], v5 offset:25088
	ds_read_b128 v[176:179], v5 offset:25344
	ds_read_b128 v[180:183], v5 offset:25600
	ds_read_b32 v184, v9 offset:24576
	ds_read_b128 v[186:189], v5 offset:26112
	v_add_f32_dpp v146, v146, v146 quad_perm:[1,0,3,2] row_mask:0xf bank_mask:0xf bound_ctrl:1
	v_pk_mul_f32 v[202:203], v[138:139], v[202:203]
	v_pk_fma_f32 v[202:203], v[140:141], v[204:205], v[202:203]
	v_add_f32_dpp v146, v146, v146 quad_perm:[2,3,0,1] row_mask:0xf bank_mask:0xf bound_ctrl:1
	s_waitcnt lgkmcnt(12)
	v_pk_mul_f32 v[220:221], v[220:221], v[228:229] op_sel_hi:[1,0]
	v_add_f32_dpp v146, v146, v146 row_half_mirror row_mask:0xf bank_mask:0xf bound_ctrl:1
	v_pk_mul_f32 v[222:223], v[222:223], v[228:229] op_sel_hi:[1,0]
	v_add_f32 v161, v202, v203
	v_add_f32_dpp v146, v146, v146 row_mirror row_mask:0xf bank_mask:0xf bound_ctrl:1
	v_pk_fma_f32 v[220:221], v[146:147], v[212:213], v[220:221] op_sel_hi:[0,1,1] neg_lo:[1,0,0] neg_hi:[1,0,0]
	v_pk_fma_f32 v[222:223], v[146:147], v[214:215], v[222:223] op_sel_hi:[0,1,1] neg_lo:[1,0,0] neg_hi:[1,0,0]
	v_pk_fma_f32 v[138:139], v[138:139], v[216:217], v[220:221]
	v_pk_fma_f32 v[140:141], v[140:141], v[218:219], v[222:223]
	v_pk_mul_f32 v[144:145], v[138:139], v[230:231]
	v_pk_fma_f32 v[144:145], v[140:141], v[232:233], v[144:145]
	v_add_f32 v146, v144, v145
	ds_read_b128 v[190:193], v5 offset:26368
	ds_read_b128 v[194:197], v5 offset:26624
	ds_read_b128 v[198:201], v5 offset:26880
	ds_read_b128 v[202:205], v5 offset:27136
	ds_read_b32 v206, v9 offset:26112
	ds_read_b128 v[208:211], v5 offset:27648
	v_add_f32_dpp v146, v146, v146 quad_perm:[1,0,3,2] row_mask:0xf bank_mask:0xf bound_ctrl:1
	v_pk_mul_f32 v[224:225], v[138:139], v[224:225]
	v_pk_fma_f32 v[224:225], v[140:141], v[226:227], v[224:225]
	v_add_f32_dpp v146, v146, v146 quad_perm:[2,3,0,1] row_mask:0xf bank_mask:0xf bound_ctrl:1
	s_waitcnt lgkmcnt(12)
	v_pk_mul_f32 v[242:243], v[242:243], v[250:251] op_sel_hi:[1,0]
	v_add_f32_dpp v146, v146, v146 row_half_mirror row_mask:0xf bank_mask:0xf bound_ctrl:1
	v_pk_mul_f32 v[244:245], v[244:245], v[250:251] op_sel_hi:[1,0]
	v_add_f32 v162, v224, v225
	v_add_f32_dpp v146, v146, v146 row_mirror row_mask:0xf bank_mask:0xf bound_ctrl:1
	v_pk_fma_f32 v[242:243], v[146:147], v[234:235], v[242:243] op_sel_hi:[0,1,1] neg_lo:[1,0,0] neg_hi:[1,0,0]
	v_pk_fma_f32 v[244:245], v[146:147], v[236:237], v[244:245] op_sel_hi:[0,1,1] neg_lo:[1,0,0] neg_hi:[1,0,0]
	v_pk_fma_f32 v[138:139], v[138:139], v[238:239], v[242:243]
	v_pk_fma_f32 v[140:141], v[140:141], v[240:241], v[244:245]
	v_pk_mul_f32 v[144:145], v[138:139], v[164:165]
	v_pk_fma_f32 v[144:145], v[140:141], v[166:167], v[144:145]
	v_add_f32 v146, v144, v145
	ds_read_b128 v[212:215], v5 offset:27904
	ds_read_b128 v[216:219], v5 offset:28160
	ds_read_b128 v[220:223], v5 offset:28416
	ds_read_b128 v[224:227], v5 offset:28672
	ds_read_b32 v228, v9 offset:27648
	ds_read_b128 v[230:233], v5 offset:29184
	v_add_f32_dpp v146, v146, v146 quad_perm:[1,0,3,2] row_mask:0xf bank_mask:0xf bound_ctrl:1
	v_pk_mul_f32 v[246:247], v[138:139], v[246:247]
	v_pk_fma_f32 v[246:247], v[140:141], v[248:249], v[246:247]
	v_add_f32_dpp v146, v146, v146 quad_perm:[2,3,0,1] row_mask:0xf bank_mask:0xf bound_ctrl:1
	s_waitcnt lgkmcnt(12)
	v_pk_mul_f32 v[176:177], v[176:177], v[184:185] op_sel_hi:[1,0]
	v_add_f32_dpp v146, v146, v146 row_half_mirror row_mask:0xf bank_mask:0xf bound_ctrl:1
	v_pk_mul_f32 v[178:179], v[178:179], v[184:185] op_sel_hi:[1,0]
	v_add_f32 v163, v246, v247
	v_add_f32_dpp v146, v146, v146 row_mirror row_mask:0xf bank_mask:0xf bound_ctrl:1
	v_pk_fma_f32 v[176:177], v[146:147], v[168:169], v[176:177] op_sel_hi:[0,1,1] neg_lo:[1,0,0] neg_hi:[1,0,0]
	v_pk_fma_f32 v[178:179], v[146:147], v[170:171], v[178:179] op_sel_hi:[0,1,1] neg_lo:[1,0,0] neg_hi:[1,0,0]
	v_pk_fma_f32 v[138:139], v[138:139], v[172:173], v[176:177]
	v_pk_fma_f32 v[140:141], v[140:141], v[174:175], v[178:179]
	v_pk_mul_f32 v[144:145], v[138:139], v[186:187]
	v_pk_fma_f32 v[144:145], v[140:141], v[188:189], v[144:145]
	v_add_f32 v146, v144, v145
	v_add_f32_dpp v102, v148, v148 row_mirror row_mask:0xf bank_mask:0x3 bound_ctrl:1
	v_add_f32_dpp v102, v156, v156 row_mirror row_mask:0xf bank_mask:0xc bound_ctrl:1
	v_add_f32_dpp v103, v149, v149 row_mirror row_mask:0xf bank_mask:0x3 bound_ctrl:1
	v_add_f32_dpp v103, v157, v157 row_mirror row_mask:0xf bank_mask:0xc bound_ctrl:1
	v_add_f32_dpp v104, v150, v150 row_mirror row_mask:0xf bank_mask:0x3 bound_ctrl:1
	v_add_f32_dpp v104, v158, v158 row_mirror row_mask:0xf bank_mask:0xc bound_ctrl:1
	v_add_f32_dpp v105, v151, v151 row_mirror row_mask:0xf bank_mask:0x3 bound_ctrl:1
	v_add_f32_dpp v105, v159, v159 row_mirror row_mask:0xf bank_mask:0xc bound_ctrl:1
	v_add_f32_dpp v106, v152, v152 row_mirror row_mask:0xf bank_mask:0x3 bound_ctrl:1
	v_add_f32_dpp v106, v160, v160 row_mirror row_mask:0xf bank_mask:0xc bound_ctrl:1
	v_add_f32_dpp v107, v153, v153 row_mirror row_mask:0xf bank_mask:0x3 bound_ctrl:1
	v_add_f32_dpp v107, v161, v161 row_mirror row_mask:0xf bank_mask:0xc bound_ctrl:1
	v_add_f32_dpp v108, v154, v154 row_mirror row_mask:0xf bank_mask:0x3 bound_ctrl:1
	v_add_f32_dpp v108, v162, v162 row_mirror row_mask:0xf bank_mask:0xc bound_ctrl:1
	v_add_f32_dpp v109, v155, v155 row_mirror row_mask:0xf bank_mask:0x3 bound_ctrl:1
	v_add_f32_dpp v109, v163, v163 row_mirror row_mask:0xf bank_mask:0xc bound_ctrl:1
	v_add_f32_dpp v110, v102, v102 row_half_mirror row_mask:0xf bank_mask:0x5 bound_ctrl:1
	v_add_f32_dpp v110, v106, v106 row_half_mirror row_mask:0xf bank_mask:0xa bound_ctrl:1
	v_add_f32_dpp v111, v103, v103 row_half_mirror row_mask:0xf bank_mask:0x5 bound_ctrl:1
	v_add_f32_dpp v111, v107, v107 row_half_mirror row_mask:0xf bank_mask:0xa bound_ctrl:1
	v_add_f32_dpp v112, v104, v104 row_half_mirror row_mask:0xf bank_mask:0x5 bound_ctrl:1
	v_add_f32_dpp v112, v108, v108 row_half_mirror row_mask:0xf bank_mask:0xa bound_ctrl:1
	v_add_f32_dpp v113, v105, v105 row_half_mirror row_mask:0xf bank_mask:0x5 bound_ctrl:1
	v_add_f32_dpp v113, v109, v109 row_half_mirror row_mask:0xf bank_mask:0xa bound_ctrl:1
	s_mov_b32 vcc_lo, 0xcccccccc
	s_mov_b32 vcc_hi, 0xcccccccc
	v_cndmask_b32 v116, v112, v110, vcc
	v_cndmask_b32 v117, v113, v111, vcc
	v_cndmask_b32 v114, v110, v112, vcc
	v_cndmask_b32 v115, v111, v113, vcc
	v_add_f32_dpp v114, v116, v114 quad_perm:[2,3,0,1] row_mask:0xf bank_mask:0xf bound_ctrl:1
	v_add_f32_dpp v115, v117, v115 quad_perm:[2,3,0,1] row_mask:0xf bank_mask:0xf bound_ctrl:1
	s_mov_b32 vcc_lo, 0xaaaaaaaa
	s_mov_b32 vcc_hi, 0xaaaaaaaa
	v_cndmask_b32 v116, v115, v114, vcc
	v_cndmask_b32 v117, v114, v115, vcc
	s_nop 0
	v_add_f32_dpp v18, v116, v117 quad_perm:[1,0,3,2] row_mask:0xf bank_mask:0xf bound_ctrl:1
	ds_read_b128 v[234:237], v5 offset:29440
	ds_read_b128 v[238:241], v5 offset:29696
	ds_read_b128 v[242:245], v5 offset:29952
	ds_read_b128 v[246:249], v5 offset:30208
	ds_read_b32 v250, v9 offset:29184
	ds_read_b128 v[164:167], v5 offset:30720
	v_add_f32_dpp v146, v146, v146 quad_perm:[1,0,3,2] row_mask:0xf bank_mask:0xf bound_ctrl:1
	v_pk_mul_f32 v[180:181], v[138:139], v[180:181]
	v_pk_fma_f32 v[180:181], v[140:141], v[182:183], v[180:181]
	v_add_f32_dpp v146, v146, v146 quad_perm:[2,3,0,1] row_mask:0xf bank_mask:0xf bound_ctrl:1
	s_waitcnt lgkmcnt(12)
	v_pk_mul_f32 v[198:199], v[198:199], v[206:207] op_sel_hi:[1,0]
	v_add_f32_dpp v146, v146, v146 row_half_mirror row_mask:0xf bank_mask:0xf bound_ctrl:1
	v_pk_mul_f32 v[200:201], v[200:201], v[206:207] op_sel_hi:[1,0]
	v_add_f32 v148, v180, v181
	v_add_f32_dpp v146, v146, v146 row_mirror row_mask:0xf bank_mask:0xf bound_ctrl:1
	v_pk_fma_f32 v[198:199], v[146:147], v[190:191], v[198:199] op_sel_hi:[0,1,1] neg_lo:[1,0,0] neg_hi:[1,0,0]
	v_pk_fma_f32 v[200:201], v[146:147], v[192:193], v[200:201] op_sel_hi:[0,1,1] neg_lo:[1,0,0] neg_hi:[1,0,0]
	v_pk_fma_f32 v[138:139], v[138:139], v[194:195], v[198:199]
	v_pk_fma_f32 v[140:141], v[140:141], v[196:197], v[200:201]
	v_pk_mul_f32 v[144:145], v[138:139], v[208:209]
	v_pk_fma_f32 v[144:145], v[140:141], v[210:211], v[144:145]
	v_add_f32 v146, v144, v145
	ds_read_b128 v[168:171], v5 offset:30976
	ds_read_b128 v[172:175], v5 offset:31232
	ds_read_b128 v[176:179], v5 offset:31488
	ds_read_b128 v[180:183], v5 offset:31744
	ds_read_b32 v184, v9 offset:30720
	ds_read_b128 v[186:189], v5 offset:32256
	v_add_f32_dpp v146, v146, v146 quad_perm:[1,0,3,2] row_mask:0xf bank_mask:0xf bound_ctrl:1
	v_pk_mul_f32 v[202:203], v[138:139], v[202:203]
	v_pk_fma_f32 v[202:203], v[140:141], v[204:205], v[202:203]
	v_add_f32_dpp v146, v146, v146 quad_perm:[2,3,0,1] row_mask:0xf bank_mask:0xf bound_ctrl:1
	s_waitcnt lgkmcnt(12)
	v_pk_mul_f32 v[220:221], v[220:221], v[228:229] op_sel_hi:[1,0]
	v_add_f32_dpp v146, v146, v146 row_half_mirror row_mask:0xf bank_mask:0xf bound_ctrl:1
	v_pk_mul_f32 v[222:223], v[222:223], v[228:229] op_sel_hi:[1,0]
	v_add_f32 v149, v202, v203
	v_add_f32_dpp v146, v146, v146 row_mirror row_mask:0xf bank_mask:0xf bound_ctrl:1
	v_pk_fma_f32 v[220:221], v[146:147], v[212:213], v[220:221] op_sel_hi:[0,1,1] neg_lo:[1,0,0] neg_hi:[1,0,0]
	v_pk_fma_f32 v[222:223], v[146:147], v[214:215], v[222:223] op_sel_hi:[0,1,1] neg_lo:[1,0,0] neg_hi:[1,0,0]
	v_pk_fma_f32 v[138:139], v[138:139], v[216:217], v[220:221]
	v_pk_fma_f32 v[140:141], v[140:141], v[218:219], v[222:223]
	v_pk_mul_f32 v[144:145], v[138:139], v[230:231]
	v_pk_fma_f32 v[144:145], v[140:141], v[232:233], v[144:145]
	v_add_f32 v146, v144, v145
	ds_read_b128 v[190:193], v5 offset:32512
	ds_read_b128 v[194:197], v5 offset:32768
	ds_read_b128 v[198:201], v5 offset:33024
	ds_read_b128 v[202:205], v5 offset:33280
	ds_read_b32 v206, v9 offset:32256
	ds_read_b128 v[208:211], v5 offset:33792
	v_add_f32_dpp v146, v146, v146 quad_perm:[1,0,3,2] row_mask:0xf bank_mask:0xf bound_ctrl:1
	v_pk_mul_f32 v[224:225], v[138:139], v[224:225]
	v_pk_fma_f32 v[224:225], v[140:141], v[226:227], v[224:225]
	v_add_f32_dpp v146, v146, v146 quad_perm:[2,3,0,1] row_mask:0xf bank_mask:0xf bound_ctrl:1
	s_waitcnt lgkmcnt(12)
	v_pk_mul_f32 v[242:243], v[242:243], v[250:251] op_sel_hi:[1,0]
	v_add_f32_dpp v146, v146, v146 row_half_mirror row_mask:0xf bank_mask:0xf bound_ctrl:1
	v_pk_mul_f32 v[244:245], v[244:245], v[250:251] op_sel_hi:[1,0]
	v_add_f32 v150, v224, v225
	v_add_f32_dpp v146, v146, v146 row_mirror row_mask:0xf bank_mask:0xf bound_ctrl:1
	v_pk_fma_f32 v[242:243], v[146:147], v[234:235], v[242:243] op_sel_hi:[0,1,1] neg_lo:[1,0,0] neg_hi:[1,0,0]
	v_pk_fma_f32 v[244:245], v[146:147], v[236:237], v[244:245] op_sel_hi:[0,1,1] neg_lo:[1,0,0] neg_hi:[1,0,0]
	v_pk_fma_f32 v[138:139], v[138:139], v[238:239], v[242:243]
	v_pk_fma_f32 v[140:141], v[140:141], v[240:241], v[244:245]
	v_pk_mul_f32 v[144:145], v[138:139], v[164:165]
	v_pk_fma_f32 v[144:145], v[140:141], v[166:167], v[144:145]
	v_add_f32 v146, v144, v145
	ds_read_b128 v[212:215], v5 offset:34048
	ds_read_b128 v[216:219], v5 offset:34304
	ds_read_b128 v[220:223], v5 offset:34560
	ds_read_b128 v[224:227], v5 offset:34816
	ds_read_b32 v228, v9 offset:33792
	ds_read_b128 v[230:233], v5 offset:35328
	v_add_f32_dpp v146, v146, v146 quad_perm:[1,0,3,2] row_mask:0xf bank_mask:0xf bound_ctrl:1
	v_pk_mul_f32 v[246:247], v[138:139], v[246:247]
	v_pk_fma_f32 v[246:247], v[140:141], v[248:249], v[246:247]
	v_add_f32_dpp v146, v146, v146 quad_perm:[2,3,0,1] row_mask:0xf bank_mask:0xf bound_ctrl:1
	s_waitcnt lgkmcnt(12)
	v_pk_mul_f32 v[176:177], v[176:177], v[184:185] op_sel_hi:[1,0]
	v_add_f32_dpp v146, v146, v146 row_half_mirror row_mask:0xf bank_mask:0xf bound_ctrl:1
	v_pk_mul_f32 v[178:179], v[178:179], v[184:185] op_sel_hi:[1,0]
	v_add_f32 v151, v246, v247
	v_add_f32_dpp v146, v146, v146 row_mirror row_mask:0xf bank_mask:0xf bound_ctrl:1
	v_pk_fma_f32 v[176:177], v[146:147], v[168:169], v[176:177] op_sel_hi:[0,1,1] neg_lo:[1,0,0] neg_hi:[1,0,0]
	v_pk_fma_f32 v[178:179], v[146:147], v[170:171], v[178:179] op_sel_hi:[0,1,1] neg_lo:[1,0,0] neg_hi:[1,0,0]
	v_pk_fma_f32 v[138:139], v[138:139], v[172:173], v[176:177]
	v_pk_fma_f32 v[140:141], v[140:141], v[174:175], v[178:179]
	v_pk_mul_f32 v[144:145], v[138:139], v[186:187]
	v_pk_fma_f32 v[144:145], v[140:141], v[188:189], v[144:145]
	v_add_f32 v146, v144, v145
	ds_read_b128 v[234:237], v5 offset:35584
	ds_read_b128 v[238:241], v5 offset:35840
	ds_read_b128 v[242:245], v5 offset:36096
	ds_read_b128 v[246:249], v5 offset:36352
	ds_read_b32 v250, v9 offset:35328
	ds_read_b128 v[164:167], v5 offset:36864
	v_add_f32_dpp v146, v146, v146 quad_perm:[1,0,3,2] row_mask:0xf bank_mask:0xf bound_ctrl:1
	v_pk_mul_f32 v[180:181], v[138:139], v[180:181]
	v_pk_fma_f32 v[180:181], v[140:141], v[182:183], v[180:181]
	v_add_f32_dpp v146, v146, v146 quad_perm:[2,3,0,1] row_mask:0xf bank_mask:0xf bound_ctrl:1
	s_waitcnt lgkmcnt(12)
	v_pk_mul_f32 v[198:199], v[198:199], v[206:207] op_sel_hi:[1,0]
	v_add_f32_dpp v146, v146, v146 row_half_mirror row_mask:0xf bank_mask:0xf bound_ctrl:1
	v_pk_mul_f32 v[200:201], v[200:201], v[206:207] op_sel_hi:[1,0]
	v_add_f32 v152, v180, v181
	v_add_f32_dpp v146, v146, v146 row_mirror row_mask:0xf bank_mask:0xf bound_ctrl:1
	v_pk_fma_f32 v[198:199], v[146:147], v[190:191], v[198:199] op_sel_hi:[0,1,1] neg_lo:[1,0,0] neg_hi:[1,0,0]
	v_pk_fma_f32 v[200:201], v[146:147], v[192:193], v[200:201] op_sel_hi:[0,1,1] neg_lo:[1,0,0] neg_hi:[1,0,0]
	v_pk_fma_f32 v[138:139], v[138:139], v[194:195], v[198:199]
	v_pk_fma_f32 v[140:141], v[140:141], v[196:197], v[200:201]
	v_pk_mul_f32 v[144:145], v[138:139], v[208:209]
	v_pk_fma_f32 v[144:145], v[140:141], v[210:211], v[144:145]
	v_add_f32 v146, v144, v145
	ds_read_b128 v[168:171], v5 offset:37120
	ds_read_b128 v[172:175], v5 offset:37376
	ds_read_b128 v[176:179], v5 offset:37632
	ds_read_b128 v[180:183], v5 offset:37888
	ds_read_b32 v184, v9 offset:36864
	ds_read_b128 v[186:189], v5 offset:38400
	v_add_f32_dpp v146, v146, v146 quad_perm:[1,0,3,2] row_mask:0xf bank_mask:0xf bound_ctrl:1
	v_pk_mul_f32 v[202:203], v[138:139], v[202:203]
	v_pk_fma_f32 v[202:203], v[140:141], v[204:205], v[202:203]
	v_add_f32_dpp v146, v146, v146 quad_perm:[2,3,0,1] row_mask:0xf bank_mask:0xf bound_ctrl:1
	s_waitcnt lgkmcnt(12)
	v_pk_mul_f32 v[220:221], v[220:221], v[228:229] op_sel_hi:[1,0]
	v_add_f32_dpp v146, v146, v146 row_half_mirror row_mask:0xf bank_mask:0xf bound_ctrl:1
	v_pk_mul_f32 v[222:223], v[222:223], v[228:229] op_sel_hi:[1,0]
	v_add_f32 v153, v202, v203
	v_add_f32_dpp v146, v146, v146 row_mirror row_mask:0xf bank_mask:0xf bound_ctrl:1
	v_pk_fma_f32 v[220:221], v[146:147], v[212:213], v[220:221] op_sel_hi:[0,1,1] neg_lo:[1,0,0] neg_hi:[1,0,0]
	v_pk_fma_f32 v[222:223], v[146:147], v[214:215], v[222:223] op_sel_hi:[0,1,1] neg_lo:[1,0,0] neg_hi:[1,0,0]
	v_pk_fma_f32 v[138:139], v[138:139], v[216:217], v[220:221]
	v_pk_fma_f32 v[140:141], v[140:141], v[218:219], v[222:223]
	v_pk_mul_f32 v[144:145], v[138:139], v[230:231]
	v_pk_fma_f32 v[144:145], v[140:141], v[232:233], v[144:145]
	v_add_f32 v146, v144, v145
	ds_read_b128 v[190:193], v5 offset:38656
	ds_read_b128 v[194:197], v5 offset:38912
	ds_read_b128 v[198:201], v5 offset:39168
	ds_read_b128 v[202:205], v5 offset:39424
	ds_read_b32 v206, v9 offset:38400
	ds_read_b128 v[208:211], v5 offset:39936
	v_add_f32_dpp v146, v146, v146 quad_perm:[1,0,3,2] row_mask:0xf bank_mask:0xf bound_ctrl:1
	v_pk_mul_f32 v[224:225], v[138:139], v[224:225]
	v_pk_fma_f32 v[224:225], v[140:141], v[226:227], v[224:225]
	v_add_f32_dpp v146, v146, v146 quad_perm:[2,3,0,1] row_mask:0xf bank_mask:0xf bound_ctrl:1
	s_waitcnt lgkmcnt(12)
	v_pk_mul_f32 v[242:243], v[242:243], v[250:251] op_sel_hi:[1,0]
	v_add_f32_dpp v146, v146, v146 row_half_mirror row_mask:0xf bank_mask:0xf bound_ctrl:1
	v_pk_mul_f32 v[244:245], v[244:245], v[250:251] op_sel_hi:[1,0]
	v_add_f32 v154, v224, v225
	v_add_f32_dpp v146, v146, v146 row_mirror row_mask:0xf bank_mask:0xf bound_ctrl:1
	v_pk_fma_f32 v[242:243], v[146:147], v[234:235], v[242:243] op_sel_hi:[0,1,1] neg_lo:[1,0,0] neg_hi:[1,0,0]
	v_pk_fma_f32 v[244:245], v[146:147], v[236:237], v[244:245] op_sel_hi:[0,1,1] neg_lo:[1,0,0] neg_hi:[1,0,0]
	v_pk_fma_f32 v[138:139], v[138:139], v[238:239], v[242:243]
	v_pk_fma_f32 v[140:141], v[140:141], v[240:241], v[244:245]
	v_pk_mul_f32 v[144:145], v[138:139], v[164:165]
	v_pk_fma_f32 v[144:145], v[140:141], v[166:167], v[144:145]
	v_add_f32 v146, v144, v145
	ds_read_b128 v[212:215], v5 offset:40192
	ds_read_b128 v[216:219], v5 offset:40448
	ds_read_b128 v[220:223], v5 offset:40704
	ds_read_b128 v[224:227], v5 offset:40960
	ds_read_b32 v228, v9 offset:39936
	ds_read_b128 v[230:233], v5 offset:41472
	v_add_f32_dpp v146, v146, v146 quad_perm:[1,0,3,2] row_mask:0xf bank_mask:0xf bound_ctrl:1
	v_pk_mul_f32 v[246:247], v[138:139], v[246:247]
	v_pk_fma_f32 v[246:247], v[140:141], v[248:249], v[246:247]
	v_add_f32_dpp v146, v146, v146 quad_perm:[2,3,0,1] row_mask:0xf bank_mask:0xf bound_ctrl:1
	s_waitcnt lgkmcnt(12)
	v_pk_mul_f32 v[176:177], v[176:177], v[184:185] op_sel_hi:[1,0]
	v_add_f32_dpp v146, v146, v146 row_half_mirror row_mask:0xf bank_mask:0xf bound_ctrl:1
	v_pk_mul_f32 v[178:179], v[178:179], v[184:185] op_sel_hi:[1,0]
	v_add_f32 v155, v246, v247
	v_add_f32_dpp v146, v146, v146 row_mirror row_mask:0xf bank_mask:0xf bound_ctrl:1
	v_pk_fma_f32 v[176:177], v[146:147], v[168:169], v[176:177] op_sel_hi:[0,1,1] neg_lo:[1,0,0] neg_hi:[1,0,0]
	v_pk_fma_f32 v[178:179], v[146:147], v[170:171], v[178:179] op_sel_hi:[0,1,1] neg_lo:[1,0,0] neg_hi:[1,0,0]
	v_pk_fma_f32 v[138:139], v[138:139], v[172:173], v[176:177]
	v_pk_fma_f32 v[140:141], v[140:141], v[174:175], v[178:179]
	v_pk_mul_f32 v[144:145], v[138:139], v[186:187]
	v_pk_fma_f32 v[144:145], v[140:141], v[188:189], v[144:145]
	v_add_f32 v146, v144, v145
	ds_read_b128 v[234:237], v5 offset:41728
	ds_read_b128 v[238:241], v5 offset:41984
	ds_read_b128 v[242:245], v5 offset:42240
	ds_read_b128 v[246:249], v5 offset:42496
	ds_read_b32 v250, v9 offset:41472
	ds_read_b128 v[164:167], v5 offset:43008
	v_add_f32_dpp v146, v146, v146 quad_perm:[1,0,3,2] row_mask:0xf bank_mask:0xf bound_ctrl:1
	v_pk_mul_f32 v[180:181], v[138:139], v[180:181]
	v_pk_fma_f32 v[180:181], v[140:141], v[182:183], v[180:181]
	v_add_f32_dpp v146, v146, v146 quad_perm:[2,3,0,1] row_mask:0xf bank_mask:0xf bound_ctrl:1
	s_waitcnt lgkmcnt(12)
	v_pk_mul_f32 v[198:199], v[198:199], v[206:207] op_sel_hi:[1,0]
	v_add_f32_dpp v146, v146, v146 row_half_mirror row_mask:0xf bank_mask:0xf bound_ctrl:1
	v_pk_mul_f32 v[200:201], v[200:201], v[206:207] op_sel_hi:[1,0]
	v_add_f32 v156, v180, v181
	v_add_f32_dpp v146, v146, v146 row_mirror row_mask:0xf bank_mask:0xf bound_ctrl:1
	v_pk_fma_f32 v[198:199], v[146:147], v[190:191], v[198:199] op_sel_hi:[0,1,1] neg_lo:[1,0,0] neg_hi:[1,0,0]
	v_pk_fma_f32 v[200:201], v[146:147], v[192:193], v[200:201] op_sel_hi:[0,1,1] neg_lo:[1,0,0] neg_hi:[1,0,0]
	v_pk_fma_f32 v[138:139], v[138:139], v[194:195], v[198:199]
	v_pk_fma_f32 v[140:141], v[140:141], v[196:197], v[200:201]
	v_pk_mul_f32 v[144:145], v[138:139], v[208:209]
	v_pk_fma_f32 v[144:145], v[140:141], v[210:211], v[144:145]
	v_add_f32 v146, v144, v145
	ds_read_b128 v[168:171], v5 offset:43264
	ds_read_b128 v[172:175], v5 offset:43520
	ds_read_b128 v[176:179], v5 offset:43776
	ds_read_b128 v[180:183], v5 offset:44032
	ds_read_b32 v184, v9 offset:43008
	ds_read_b128 v[186:189], v5 offset:44544
	v_add_f32_dpp v146, v146, v146 quad_perm:[1,0,3,2] row_mask:0xf bank_mask:0xf bound_ctrl:1
	v_pk_mul_f32 v[202:203], v[138:139], v[202:203]
	v_pk_fma_f32 v[202:203], v[140:141], v[204:205], v[202:203]
	v_add_f32_dpp v146, v146, v146 quad_perm:[2,3,0,1] row_mask:0xf bank_mask:0xf bound_ctrl:1
	s_waitcnt lgkmcnt(12)
	v_pk_mul_f32 v[220:221], v[220:221], v[228:229] op_sel_hi:[1,0]
	v_add_f32_dpp v146, v146, v146 row_half_mirror row_mask:0xf bank_mask:0xf bound_ctrl:1
	v_pk_mul_f32 v[222:223], v[222:223], v[228:229] op_sel_hi:[1,0]
	v_add_f32 v157, v202, v203
	v_add_f32_dpp v146, v146, v146 row_mirror row_mask:0xf bank_mask:0xf bound_ctrl:1
	v_pk_fma_f32 v[220:221], v[146:147], v[212:213], v[220:221] op_sel_hi:[0,1,1] neg_lo:[1,0,0] neg_hi:[1,0,0]
	v_pk_fma_f32 v[222:223], v[146:147], v[214:215], v[222:223] op_sel_hi:[0,1,1] neg_lo:[1,0,0] neg_hi:[1,0,0]
	v_pk_fma_f32 v[138:139], v[138:139], v[216:217], v[220:221]
	v_pk_fma_f32 v[140:141], v[140:141], v[218:219], v[222:223]
	v_pk_mul_f32 v[144:145], v[138:139], v[230:231]
	v_pk_fma_f32 v[144:145], v[140:141], v[232:233], v[144:145]
	v_add_f32 v146, v144, v145
	ds_read_b128 v[190:193], v5 offset:44800
	ds_read_b128 v[194:197], v5 offset:45056
	ds_read_b128 v[198:201], v5 offset:45312
	ds_read_b128 v[202:205], v5 offset:45568
	ds_read_b32 v206, v9 offset:44544
	ds_read_b128 v[208:211], v5 offset:46080
	v_add_f32_dpp v146, v146, v146 quad_perm:[1,0,3,2] row_mask:0xf bank_mask:0xf bound_ctrl:1
	v_pk_mul_f32 v[224:225], v[138:139], v[224:225]
	v_pk_fma_f32 v[224:225], v[140:141], v[226:227], v[224:225]
	v_add_f32_dpp v146, v146, v146 quad_perm:[2,3,0,1] row_mask:0xf bank_mask:0xf bound_ctrl:1
	s_waitcnt lgkmcnt(12)
	v_pk_mul_f32 v[242:243], v[242:243], v[250:251] op_sel_hi:[1,0]
	v_add_f32_dpp v146, v146, v146 row_half_mirror row_mask:0xf bank_mask:0xf bound_ctrl:1
	v_pk_mul_f32 v[244:245], v[244:245], v[250:251] op_sel_hi:[1,0]
	v_add_f32 v158, v224, v225
	v_add_f32_dpp v146, v146, v146 row_mirror row_mask:0xf bank_mask:0xf bound_ctrl:1
	v_pk_fma_f32 v[242:243], v[146:147], v[234:235], v[242:243] op_sel_hi:[0,1,1] neg_lo:[1,0,0] neg_hi:[1,0,0]
	v_pk_fma_f32 v[244:245], v[146:147], v[236:237], v[244:245] op_sel_hi:[0,1,1] neg_lo:[1,0,0] neg_hi:[1,0,0]
	v_pk_fma_f32 v[138:139], v[138:139], v[238:239], v[242:243]
	v_pk_fma_f32 v[140:141], v[140:141], v[240:241], v[244:245]
	v_pk_mul_f32 v[144:145], v[138:139], v[164:165]
	v_pk_fma_f32 v[144:145], v[140:141], v[166:167], v[144:145]
	v_add_f32 v146, v144, v145
	ds_read_b128 v[212:215], v5 offset:46336
	ds_read_b128 v[216:219], v5 offset:46592
	ds_read_b128 v[220:223], v5 offset:46848
	ds_read_b128 v[224:227], v5 offset:47104
	ds_read_b32 v228, v9 offset:46080
	ds_read_b128 v[230:233], v5 offset:47616
	v_add_f32_dpp v146, v146, v146 quad_perm:[1,0,3,2] row_mask:0xf bank_mask:0xf bound_ctrl:1
	v_pk_mul_f32 v[246:247], v[138:139], v[246:247]
	v_pk_fma_f32 v[246:247], v[140:141], v[248:249], v[246:247]
	v_add_f32_dpp v146, v146, v146 quad_perm:[2,3,0,1] row_mask:0xf bank_mask:0xf bound_ctrl:1
	s_waitcnt lgkmcnt(12)
	v_pk_mul_f32 v[176:177], v[176:177], v[184:185] op_sel_hi:[1,0]
	v_add_f32_dpp v146, v146, v146 row_half_mirror row_mask:0xf bank_mask:0xf bound_ctrl:1
	v_pk_mul_f32 v[178:179], v[178:179], v[184:185] op_sel_hi:[1,0]
	v_add_f32 v159, v246, v247
	v_add_f32_dpp v146, v146, v146 row_mirror row_mask:0xf bank_mask:0xf bound_ctrl:1
	v_pk_fma_f32 v[176:177], v[146:147], v[168:169], v[176:177] op_sel_hi:[0,1,1] neg_lo:[1,0,0] neg_hi:[1,0,0]
	v_pk_fma_f32 v[178:179], v[146:147], v[170:171], v[178:179] op_sel_hi:[0,1,1] neg_lo:[1,0,0] neg_hi:[1,0,0]
	v_pk_fma_f32 v[138:139], v[138:139], v[172:173], v[176:177]
	v_pk_fma_f32 v[140:141], v[140:141], v[174:175], v[178:179]
	v_pk_mul_f32 v[144:145], v[138:139], v[186:187]
	v_pk_fma_f32 v[144:145], v[140:141], v[188:189], v[144:145]
	v_add_f32 v146, v144, v145
	ds_read_b128 v[234:237], v5 offset:47872
	ds_read_b128 v[238:241], v5 offset:48128
	ds_read_b128 v[242:245], v5 offset:48384
	ds_read_b128 v[246:249], v5 offset:48640
	ds_read_b32 v250, v9 offset:47616
	v_add_f32_dpp v146, v146, v146 quad_perm:[1,0,3,2] row_mask:0xf bank_mask:0xf bound_ctrl:1
	v_pk_mul_f32 v[180:181], v[138:139], v[180:181]
	v_pk_fma_f32 v[180:181], v[140:141], v[182:183], v[180:181]
	v_add_f32_dpp v146, v146, v146 quad_perm:[2,3,0,1] row_mask:0xf bank_mask:0xf bound_ctrl:1
	s_waitcnt lgkmcnt(11)
; #define SCAN_BAR() asm volatile("s_barrier" ::: "memory")
; __device__ __forceinline__ void scan_unit(const Ctx& C0, const float* scn, int T, int quarter, const float* S0, float* Sout, unsigned char* obase, int mode) {
;     ...
;         for (int k = 0; k < nch; ++k) {
;             const unsigned aq = (unsigned)(size_t)(C.lds + (k & 1) * SLOT_B) + 16u * (unsigned)q, av = (unsigned)(size_t)(C.lds + (k & 1) * SLOT_B) + (320u + (unsigned)irow) * 4u;
;             float osel0, osel1;
;             asm volatile(SCAN_CHUNK_ASM : "+v"(S0x), "+v"(S1x), "+v"(S2x), "+v"(S3x), "=&v"(osel0), "=&v"(osel1) : "v"(aq), "v"(av), "v"(q) : SCAN_CHUNK_CLOBBERS, "memory");
;             if (mode == 0) { *(float*)(obase + (size_t)(k * 32 + q) * UPITCH_B + rl * 4) = osel0; *(float*)(obase + (size_t)(k * 32 + 16 + q) * UPITCH_B + rl * 4) = osel1; }
;             SCAN_BAR();
	v_pk_mul_f32 v[198:199], v[198:199], v[206:207] op_sel_hi:[1,0]
	v_add_f32_dpp v146, v146, v146 row_half_mirror row_mask:0xf bank_mask:0xf bound_ctrl:1
	v_pk_mul_f32 v[200:201], v[200:201], v[206:207] op_sel_hi:[1,0]
	v_add_f32 v160, v180, v181
	v_add_f32_dpp v146, v146, v146 row_mirror row_mask:0xf bank_mask:0xf bound_ctrl:1
	v_pk_fma_f32 v[198:199], v[146:147], v[190:191], v[198:199] op_sel_hi:[0,1,1] neg_lo:[1,0,0] neg_hi:[1,0,0]
	v_pk_fma_f32 v[200:201], v[146:147], v[192:193], v[200:201] op_sel_hi:[0,1,1] neg_lo:[1,0,0] neg_hi:[1,0,0]
	v_pk_fma_f32 v[138:139], v[138:139], v[194:195], v[198:199]
	v_pk_fma_f32 v[140:141], v[140:141], v[196:197], v[200:201]
	v_pk_mul_f32 v[144:145], v[138:139], v[208:209]
	v_pk_fma_f32 v[144:145], v[140:141], v[210:211], v[144:145]
	v_add_f32 v146, v144, v145
	s_nop 1
	v_add_f32_dpp v146, v146, v146 quad_perm:[1,0,3,2] row_mask:0xf bank_mask:0xf bound_ctrl:1
	v_pk_mul_f32 v[202:203], v[138:139], v[202:203]
	v_pk_fma_f32 v[202:203], v[140:141], v[204:205], v[202:203]
	v_add_f32_dpp v146, v146, v146 quad_perm:[2,3,0,1] row_mask:0xf bank_mask:0xf bound_ctrl:1
	s_waitcnt lgkmcnt(5)
	v_pk_mul_f32 v[220:221], v[220:221], v[228:229] op_sel_hi:[1,0]
	v_add_f32_dpp v146, v146, v146 row_half_mirror row_mask:0xf bank_mask:0xf bound_ctrl:1
	v_pk_mul_f32 v[222:223], v[222:223], v[228:229] op_sel_hi:[1,0]
	v_add_f32 v161, v202, v203
	v_add_f32_dpp v146, v146, v146 row_mirror row_mask:0xf bank_mask:0xf bound_ctrl:1
	v_pk_fma_f32 v[220:221], v[146:147], v[212:213], v[220:221] op_sel_hi:[0,1,1] neg_lo:[1,0,0] neg_hi:[1,0,0]
	v_pk_fma_f32 v[222:223], v[146:147], v[214:215], v[222:223] op_sel_hi:[0,1,1] neg_lo:[1,0,0] neg_hi:[1,0,0]
	v_pk_fma_f32 v[138:139], v[138:139], v[216:217], v[220:221]
	v_pk_fma_f32 v[140:141], v[140:141], v[218:219], v[222:223]
	v_pk_mul_f32 v[144:145], v[138:139], v[230:231]
	v_pk_fma_f32 v[144:145], v[140:141], v[232:233], v[144:145]
	v_add_f32 v146, v144, v145
	s_nop 1
	v_add_f32_dpp v146, v146, v146 quad_perm:[1,0,3,2] row_mask:0xf bank_mask:0xf bound_ctrl:1
	v_pk_mul_f32 v[224:225], v[138:139], v[224:225]
	v_pk_fma_f32 v[224:225], v[140:141], v[226:227], v[224:225]
	v_add_f32_dpp v146, v146, v146 quad_perm:[2,3,0,1] row_mask:0xf bank_mask:0xf bound_ctrl:1
	s_waitcnt lgkmcnt(0)
	v_pk_mul_f32 v[242:243], v[242:243], v[250:251] op_sel_hi:[1,0]
	v_add_f32_dpp v146, v146, v146 row_half_mirror row_mask:0xf bank_mask:0xf bound_ctrl:1
	v_pk_mul_f32 v[244:245], v[244:245], v[250:251] op_sel_hi:[1,0]
	v_add_f32 v162, v224, v225
	v_add_f32_dpp v146, v146, v146 row_mirror row_mask:0xf bank_mask:0xf bound_ctrl:1
	v_pk_fma_f32 v[242:243], v[146:147], v[234:235], v[242:243] op_sel_hi:[0,1,1] neg_lo:[1,0,0] neg_hi:[1,0,0]
	v_pk_fma_f32 v[244:245], v[146:147], v[236:237], v[244:245] op_sel_hi:[0,1,1] neg_lo:[1,0,0] neg_hi:[1,0,0]
	v_pk_fma_f32 v[138:139], v[138:139], v[238:239], v[242:243]
	v_pk_fma_f32 v[140:141], v[140:141], v[240:241], v[244:245]
	s_barrier
	ds_read_b128 v[164:167], v10 offset:0
	ds_read_b128 v[168:171], v10 offset:256
	ds_read_b128 v[172:175], v10 offset:512
	ds_read_b128 v[176:179], v10 offset:768
	ds_read_b128 v[180:183], v10 offset:1024
	ds_read_b32 v184, v11 offset:0
	ds_read_b128 v[186:189], v10 offset:1536
	ds_read_b128 v[190:193], v10 offset:1792
	ds_read_b128 v[194:197], v10 offset:2048
	ds_read_b128 v[198:201], v10 offset:2304
	ds_read_b128 v[202:205], v10 offset:2560
	ds_read_b32 v206, v11 offset:1536
	ds_read_b128 v[208:211], v10 offset:3072
	v_pk_mul_f32 v[246:247], v[138:139], v[246:247]
	v_pk_fma_f32 v[246:247], v[140:141], v[248:249], v[246:247]
	v_add_f32 v163, v246, v247
	s_nop 0
	v_add_f32_dpp v102, v148, v148 row_mirror row_mask:0xf bank_mask:0x3 bound_ctrl:1
	v_add_f32_dpp v102, v156, v156 row_mirror row_mask:0xf bank_mask:0xc bound_ctrl:1
	v_add_f32_dpp v103, v149, v149 row_mirror row_mask:0xf bank_mask:0x3 bound_ctrl:1
	v_add_f32_dpp v103, v157, v157 row_mirror row_mask:0xf bank_mask:0xc bound_ctrl:1
	v_add_f32_dpp v104, v150, v150 row_mirror row_mask:0xf bank_mask:0x3 bound_ctrl:1
	v_add_f32_dpp v104, v158, v158 row_mirror row_mask:0xf bank_mask:0xc bound_ctrl:1
	v_add_f32_dpp v105, v151, v151 row_mirror row_mask:0xf bank_mask:0x3 bound_ctrl:1
	v_add_f32_dpp v105, v159, v159 row_mirror row_mask:0xf bank_mask:0xc bound_ctrl:1
	v_add_f32_dpp v106, v152, v152 row_mirror row_mask:0xf bank_mask:0x3 bound_ctrl:1
	v_add_f32_dpp v106, v160, v160 row_mirror row_mask:0xf bank_mask:0xc bound_ctrl:1
	v_add_f32_dpp v107, v153, v153 row_mirror row_mask:0xf bank_mask:0x3 bound_ctrl:1
	v_add_f32_dpp v107, v161, v161 row_mirror row_mask:0xf bank_mask:0xc bound_ctrl:1
	v_add_f32_dpp v108, v154, v154 row_mirror row_mask:0xf bank_mask:0x3 bound_ctrl:1
	v_add_f32_dpp v108, v162, v162 row_mirror row_mask:0xf bank_mask:0xc bound_ctrl:1
	v_add_f32_dpp v109, v155, v155 row_mirror row_mask:0xf bank_mask:0x3 bound_ctrl:1
	v_add_f32_dpp v109, v163, v163 row_mirror row_mask:0xf bank_mask:0xc bound_ctrl:1
	v_add_f32_dpp v110, v102, v102 row_half_mirror row_mask:0xf bank_mask:0x5 bound_ctrl:1
	v_add_f32_dpp v110, v106, v106 row_half_mirror row_mask:0xf bank_mask:0xa bound_ctrl:1
	v_add_f32_dpp v111, v103, v103 row_half_mirror row_mask:0xf bank_mask:0x5 bound_ctrl:1
	v_add_f32_dpp v111, v107, v107 row_half_mirror row_mask:0xf bank_mask:0xa bound_ctrl:1
	v_add_f32_dpp v112, v104, v104 row_half_mirror row_mask:0xf bank_mask:0x5 bound_ctrl:1
	v_add_f32_dpp v112, v108, v108 row_half_mirror row_mask:0xf bank_mask:0xa bound_ctrl:1
	v_add_f32_dpp v113, v105, v105 row_half_mirror row_mask:0xf bank_mask:0x5 bound_ctrl:1
	v_add_f32_dpp v113, v109, v109 row_half_mirror row_mask:0xf bank_mask:0xa bound_ctrl:1
	s_mov_b32 vcc_lo, 0xcccccccc
	s_mov_b32 vcc_hi, 0xcccccccc
	v_cndmask_b32 v116, v112, v110, vcc
	v_cndmask_b32 v117, v113, v111, vcc
	v_cndmask_b32 v114, v110, v112, vcc
	v_cndmask_b32 v115, v111, v113, vcc
	v_add_f32_dpp v114, v116, v114 quad_perm:[2,3,0,1] row_mask:0xf bank_mask:0xf bound_ctrl:1
	v_add_f32_dpp v115, v117, v115 quad_perm:[2,3,0,1] row_mask:0xf bank_mask:0xf bound_ctrl:1
	s_mov_b32 vcc_lo, 0xaaaaaaaa
	s_mov_b32 vcc_hi, 0xaaaaaaaa
	v_cndmask_b32 v116, v115, v114, vcc
	v_cndmask_b32 v117, v114, v115, vcc
	s_nop 0
	v_add_f32_dpp v19, v116, v117 quad_perm:[1,0,3,2] row_mask:0xf bank_mask:0xf bound_ctrl:1

; #define SCAN_BAR() asm volatile("s_barrier" ::: "memory")
; __device__ __forceinline__ void scan_unit(const Ctx& C0, const float* scn, int T, int quarter, const float* S0, float* Sout, unsigned char* obase, int mode) {
;     ...
;             if (mode == 0) { *(float*)(obase + (size_t)(k * 32 + q) * UPITCH_B + rl * 4) = osel0; *(float*)(obase + (size_t)(k * 32 + 16 + q) * UPITCH_B + rl * 4) = osel1; }
;             SCAN_BAR();
	v_lshl_add_u64 v[14:15], v[6:7], 0, s[0:1]
	v_add_co_u32_e32 v16, vcc, 0xfc29000, v14
	s_mov_b32 s8, 0xfc7f000
	s_nop 0
	v_addc_co_u32_e32 v17, vcc, 0, v15, vcc
	global_store_dword v[16:17], v18, off offset:768
	v_add_co_u32_e32 v16, vcc, 0xfc54000, v14
	s_add_u32 s0, s0, 0xac000
	s_nop 0
	v_addc_co_u32_e32 v17, vcc, 0, v15, vcc
	global_store_dword v[16:17], v19, off offset:768
	s_waitcnt lgkmcnt(12)
	v_pk_mul_f32 v[144:145], v[138:139], v[164:165]
	v_pk_fma_f32 v[144:145], v[140:141], v[166:167], v[144:145]
	v_add_f32 v146, v144, v145
	ds_read_b128 v[212:215], v10 offset:3328
	ds_read_b128 v[216:219], v10 offset:3584
	ds_read_b128 v[220:223], v10 offset:3840
	ds_read_b128 v[224:227], v10 offset:4096
	ds_read_b32 v228, v11 offset:3072
	ds_read_b128 v[230:233], v10 offset:4608
	v_add_f32_dpp v146, v146, v146 quad_perm:[1,0,3,2] row_mask:0xf bank_mask:0xf bound_ctrl:1
	s_nop 0
	s_nop 0
	v_add_f32_dpp v146, v146, v146 quad_perm:[2,3,0,1] row_mask:0xf bank_mask:0xf bound_ctrl:1
	s_waitcnt lgkmcnt(12)
	v_pk_mul_f32 v[176:177], v[176:177], v[184:185] op_sel_hi:[1,0]
	v_add_f32_dpp v146, v146, v146 row_half_mirror row_mask:0xf bank_mask:0xf bound_ctrl:1
	v_pk_mul_f32 v[178:179], v[178:179], v[184:185] op_sel_hi:[1,0]
	s_nop 0
	v_add_f32_dpp v146, v146, v146 row_mirror row_mask:0xf bank_mask:0xf bound_ctrl:1
	v_pk_fma_f32 v[176:177], v[146:147], v[168:169], v[176:177] op_sel_hi:[0,1,1] neg_lo:[1,0,0] neg_hi:[1,0,0]
	v_pk_fma_f32 v[178:179], v[146:147], v[170:171], v[178:179] op_sel_hi:[0,1,1] neg_lo:[1,0,0] neg_hi:[1,0,0]
	v_pk_fma_f32 v[138:139], v[138:139], v[172:173], v[176:177]
	v_pk_fma_f32 v[140:141], v[140:141], v[174:175], v[178:179]
	v_pk_mul_f32 v[144:145], v[138:139], v[186:187]
	v_pk_fma_f32 v[144:145], v[140:141], v[188:189], v[144:145]
	v_add_f32 v146, v144, v145
	ds_read_b128 v[234:237], v10 offset:4864
	ds_read_b128 v[238:241], v10 offset:5120
	ds_read_b128 v[242:245], v10 offset:5376
	ds_read_b128 v[246:249], v10 offset:5632
	ds_read_b32 v250, v11 offset:4608
	ds_read_b128 v[164:167], v10 offset:6144
	v_add_f32_dpp v146, v146, v146 quad_perm:[1,0,3,2] row_mask:0xf bank_mask:0xf bound_ctrl:1
	v_pk_mul_f32 v[180:181], v[138:139], v[180:181]
	v_pk_fma_f32 v[180:181], v[140:141], v[182:183], v[180:181]
	v_add_f32_dpp v146, v146, v146 quad_perm:[2,3,0,1] row_mask:0xf bank_mask:0xf bound_ctrl:1
	s_waitcnt lgkmcnt(12)
	v_pk_mul_f32 v[198:199], v[198:199], v[206:207] op_sel_hi:[1,0]
	v_add_f32_dpp v146, v146, v146 row_half_mirror row_mask:0xf bank_mask:0xf bound_ctrl:1
	v_pk_mul_f32 v[200:201], v[200:201], v[206:207] op_sel_hi:[1,0]
	v_add_f32 v148, v180, v181
	v_add_f32_dpp v146, v146, v146 row_mirror row_mask:0xf bank_mask:0xf bound_ctrl:1
	v_pk_fma_f32 v[198:199], v[146:147], v[190:191], v[198:199] op_sel_hi:[0,1,1] neg_lo:[1,0,0] neg_hi:[1,0,0]
	v_pk_fma_f32 v[200:201], v[146:147], v[192:193], v[200:201] op_sel_hi:[0,1,1] neg_lo:[1,0,0] neg_hi:[1,0,0]
	v_pk_fma_f32 v[138:139], v[138:139], v[194:195], v[198:199]
	v_pk_fma_f32 v[140:141], v[140:141], v[196:197], v[200:201]
	v_pk_mul_f32 v[144:145], v[138:139], v[208:209]
	v_pk_fma_f32 v[144:145], v[140:141], v[210:211], v[144:145]
	v_add_f32 v146, v144, v145
	ds_read_b128 v[168:171], v10 offset:6400
	ds_read_b128 v[172:175], v10 offset:6656
	ds_read_b128 v[176:179], v10 offset:6912
	ds_read_b128 v[180:183], v10 offset:7168
	ds_read_b32 v184, v11 offset:6144
	ds_read_b128 v[186:189], v10 offset:7680
	v_add_f32_dpp v146, v146, v146 quad_perm:[1,0,3,2] row_mask:0xf bank_mask:0xf bound_ctrl:1
	v_pk_mul_f32 v[202:203], v[138:139], v[202:203]
	v_pk_fma_f32 v[202:203], v[140:141], v[204:205], v[202:203]
	v_add_f32_dpp v146, v146, v146 quad_perm:[2,3,0,1] row_mask:0xf bank_mask:0xf bound_ctrl:1
	s_waitcnt lgkmcnt(12)
	v_pk_mul_f32 v[220:221], v[220:221], v[228:229] op_sel_hi:[1,0]
	v_add_f32_dpp v146, v146, v146 row_half_mirror row_mask:0xf bank_mask:0xf bound_ctrl:1
	v_pk_mul_f32 v[222:223], v[222:223], v[228:229] op_sel_hi:[1,0]
	v_add_f32 v149, v202, v203
	v_add_f32_dpp v146, v146, v146 row_mirror row_mask:0xf bank_mask:0xf bound_ctrl:1
	v_pk_fma_f32 v[220:221], v[146:147], v[212:213], v[220:221] op_sel_hi:[0,1,1] neg_lo:[1,0,0] neg_hi:[1,0,0]
	v_pk_fma_f32 v[222:223], v[146:147], v[214:215], v[222:223] op_sel_hi:[0,1,1] neg_lo:[1,0,0] neg_hi:[1,0,0]
	v_pk_fma_f32 v[138:139], v[138:139], v[216:217], v[220:221]
	v_pk_fma_f32 v[140:141], v[140:141], v[218:219], v[222:223]
	v_pk_mul_f32 v[144:145], v[138:139], v[230:231]
	v_pk_fma_f32 v[144:145], v[140:141], v[232:233], v[144:145]
	v_add_f32 v146, v144, v145
	ds_read_b128 v[190:193], v10 offset:7936
	ds_read_b128 v[194:197], v10 offset:8192
	ds_read_b128 v[198:201], v10 offset:8448
	ds_read_b128 v[202:205], v10 offset:8704
	ds_read_b32 v206, v11 offset:7680
	ds_read_b128 v[208:211], v10 offset:9216
	v_add_f32_dpp v146, v146, v146 quad_perm:[1,0,3,2] row_mask:0xf bank_mask:0xf bound_ctrl:1
	v_pk_mul_f32 v[224:225], v[138:139], v[224:225]
	v_pk_fma_f32 v[224:225], v[140:141], v[226:227], v[224:225]
	v_add_f32_dpp v146, v146, v146 quad_perm:[2,3,0,1] row_mask:0xf bank_mask:0xf bound_ctrl:1
	s_waitcnt lgkmcnt(12)
	v_pk_mul_f32 v[242:243], v[242:243], v[250:251] op_sel_hi:[1,0]
	v_add_f32_dpp v146, v146, v146 row_half_mirror row_mask:0xf bank_mask:0xf bound_ctrl:1
	v_pk_mul_f32 v[244:245], v[244:245], v[250:251] op_sel_hi:[1,0]
	v_add_f32 v150, v224, v225
	v_add_f32_dpp v146, v146, v146 row_mirror row_mask:0xf bank_mask:0xf bound_ctrl:1
	v_pk_fma_f32 v[242:243], v[146:147], v[234:235], v[242:243] op_sel_hi:[0,1,1] neg_lo:[1,0,0] neg_hi:[1,0,0]
	v_pk_fma_f32 v[244:245], v[146:147], v[236:237], v[244:245] op_sel_hi:[0,1,1] neg_lo:[1,0,0] neg_hi:[1,0,0]
	v_pk_fma_f32 v[138:139], v[138:139], v[238:239], v[242:243]
	v_pk_fma_f32 v[140:141], v[140:141], v[240:241], v[244:245]
	v_pk_mul_f32 v[144:145], v[138:139], v[164:165]
	v_pk_fma_f32 v[144:145], v[140:141], v[166:167], v[144:145]
	v_add_f32 v146, v144, v145
	ds_read_b128 v[212:215], v10 offset:9472
	ds_read_b128 v[216:219], v10 offset:9728
	ds_read_b128 v[220:223], v10 offset:9984
	ds_read_b128 v[224:227], v10 offset:10240
	ds_read_b32 v228, v11 offset:9216
	ds_read_b128 v[230:233], v10 offset:10752
	v_add_f32_dpp v146, v146, v146 quad_perm:[1,0,3,2] row_mask:0xf bank_mask:0xf bound_ctrl:1
	v_pk_mul_f32 v[246:247], v[138:139], v[246:247]
	v_pk_fma_f32 v[246:247], v[140:141], v[248:249], v[246:247]
	v_add_f32_dpp v146, v146, v146 quad_perm:[2,3,0,1] row_mask:0xf bank_mask:0xf bound_ctrl:1
	s_waitcnt lgkmcnt(12)
	v_pk_mul_f32 v[176:177], v[176:177], v[184:185] op_sel_hi:[1,0]
	v_add_f32_dpp v146, v146, v146 row_half_mirror row_mask:0xf bank_mask:0xf bound_ctrl:1
	v_pk_mul_f32 v[178:179], v[178:179], v[184:185] op_sel_hi:[1,0]
	v_add_f32 v151, v246, v247
	v_add_f32_dpp v146, v146, v146 row_mirror row_mask:0xf bank_mask:0xf bound_ctrl:1
	v_pk_fma_f32 v[176:177], v[146:147], v[168:169], v[176:177] op_sel_hi:[0,1,1] neg_lo:[1,0,0] neg_hi:[1,0,0]
	v_pk_fma_f32 v[178:179], v[146:147], v[170:171], v[178:179] op_sel_hi:[0,1,1] neg_lo:[1,0,0] neg_hi:[1,0,0]
	v_pk_fma_f32 v[138:139], v[138:139], v[172:173], v[176:177]
	v_pk_fma_f32 v[140:141], v[140:141], v[174:175], v[178:179]
	v_pk_mul_f32 v[144:145], v[138:139], v[186:187]
	v_pk_fma_f32 v[144:145], v[140:141], v[188:189], v[144:145]
	v_add_f32 v146, v144, v145
	ds_read_b128 v[234:237], v10 offset:11008
	ds_read_b128 v[238:241], v10 offset:11264
	ds_read_b128 v[242:245], v10 offset:11520
	ds_read_b128 v[246:249], v10 offset:11776
	ds_read_b32 v250, v11 offset:10752
	ds_read_b128 v[164:167], v10 offset:12288
	v_add_f32_dpp v146, v146, v146 quad_perm:[1,0,3,2] row_mask:0xf bank_mask:0xf bound_ctrl:1
	v_pk_mul_f32 v[180:181], v[138:139], v[180:181]
	v_pk_fma_f32 v[180:181], v[140:141], v[182:183], v[180:181]
	v_add_f32_dpp v146, v146, v146 quad_perm:[2,3,0,1] row_mask:0xf bank_mask:0xf bound_ctrl:1
	s_waitcnt lgkmcnt(12)
	v_pk_mul_f32 v[198:199], v[198:199], v[206:207] op_sel_hi:[1,0]
	v_add_f32_dpp v146, v146, v146 row_half_mirror row_mask:0xf bank_mask:0xf bound_ctrl:1
	v_pk_mul_f32 v[200:201], v[200:201], v[206:207] op_sel_hi:[1,0]
	v_add_f32 v152, v180, v181
	v_add_f32_dpp v146, v146, v146 row_mirror row_mask:0xf bank_mask:0xf bound_ctrl:1
	v_pk_fma_f32 v[198:199], v[146:147], v[190:191], v[198:199] op_sel_hi:[0,1,1] neg_lo:[1,0,0] neg_hi:[1,0,0]
	v_pk_fma_f32 v[200:201], v[146:147], v[192:193], v[200:201] op_sel_hi:[0,1,1] neg_lo:[1,0,0] neg_hi:[1,0,0]
	v_pk_fma_f32 v[138:139], v[138:139], v[194:195], v[198:199]
	v_pk_fma_f32 v[140:141], v[140:141], v[196:197], v[200:201]
	v_pk_mul_f32 v[144:145], v[138:139], v[208:209]
	v_pk_fma_f32 v[144:145], v[140:141], v[210:211], v[144:145]
	v_add_f32 v146, v144, v145
	ds_read_b128 v[168:171], v10 offset:12544
	ds_read_b128 v[172:175], v10 offset:12800
	ds_read_b128 v[176:179], v10 offset:13056
	ds_read_b128 v[180:183], v10 offset:13312
	ds_read_b32 v184, v11 offset:12288
	ds_read_b128 v[186:189], v10 offset:13824
	v_add_f32_dpp v146, v146, v146 quad_perm:[1,0,3,2] row_mask:0xf bank_mask:0xf bound_ctrl:1
	v_pk_mul_f32 v[202:203], v[138:139], v[202:203]
	v_pk_fma_f32 v[202:203], v[140:141], v[204:205], v[202:203]
	v_add_f32_dpp v146, v146, v146 quad_perm:[2,3,0,1] row_mask:0xf bank_mask:0xf bound_ctrl:1
	s_waitcnt lgkmcnt(12)
	v_pk_mul_f32 v[220:221], v[220:221], v[228:229] op_sel_hi:[1,0]
	v_add_f32_dpp v146, v146, v146 row_half_mirror row_mask:0xf bank_mask:0xf bound_ctrl:1
	v_pk_mul_f32 v[222:223], v[222:223], v[228:229] op_sel_hi:[1,0]
	v_add_f32 v153, v202, v203
	v_add_f32_dpp v146, v146, v146 row_mirror row_mask:0xf bank_mask:0xf bound_ctrl:1
	v_pk_fma_f32 v[220:221], v[146:147], v[212:213], v[220:221] op_sel_hi:[0,1,1] neg_lo:[1,0,0] neg_hi:[1,0,0]
	v_pk_fma_f32 v[222:223], v[146:147], v[214:215], v[222:223] op_sel_hi:[0,1,1] neg_lo:[1,0,0] neg_hi:[1,0,0]
	v_pk_fma_f32 v[138:139], v[138:139], v[216:217], v[220:221]
	v_pk_fma_f32 v[140:141], v[140:141], v[218:219], v[222:223]
	v_pk_mul_f32 v[144:145], v[138:139], v[230:231]
	v_pk_fma_f32 v[144:145], v[140:141], v[232:233], v[144:145]
	v_add_f32 v146, v144, v145
	ds_read_b128 v[190:193], v10 offset:14080
	ds_read_b128 v[194:197], v10 offset:14336
	ds_read_b128 v[198:201], v10 offset:14592
	ds_read_b128 v[202:205], v10 offset:14848
	ds_read_b32 v206, v11 offset:13824
	ds_read_b128 v[208:211], v10 offset:15360
	v_add_f32_dpp v146, v146, v146 quad_perm:[1,0,3,2] row_mask:0xf bank_mask:0xf bound_ctrl:1
	v_pk_mul_f32 v[224:225], v[138:139], v[224:225]
	v_pk_fma_f32 v[224:225], v[140:141], v[226:227], v[224:225]
	v_add_f32_dpp v146, v146, v146 quad_perm:[2,3,0,1] row_mask:0xf bank_mask:0xf bound_ctrl:1
	s_waitcnt lgkmcnt(12)
	v_pk_mul_f32 v[242:243], v[242:243], v[250:251] op_sel_hi:[1,0]
	v_add_f32_dpp v146, v146, v146 row_half_mirror row_mask:0xf bank_mask:0xf bound_ctrl:1
	v_pk_mul_f32 v[244:245], v[244:245], v[250:251] op_sel_hi:[1,0]
	v_add_f32 v154, v224, v225
	v_add_f32_dpp v146, v146, v146 row_mirror row_mask:0xf bank_mask:0xf bound_ctrl:1
	v_pk_fma_f32 v[242:243], v[146:147], v[234:235], v[242:243] op_sel_hi:[0,1,1] neg_lo:[1,0,0] neg_hi:[1,0,0]
	v_pk_fma_f32 v[244:245], v[146:147], v[236:237], v[244:245] op_sel_hi:[0,1,1] neg_lo:[1,0,0] neg_hi:[1,0,0]
	v_pk_fma_f32 v[138:139], v[138:139], v[238:239], v[242:243]
	v_pk_fma_f32 v[140:141], v[140:141], v[240:241], v[244:245]
	v_pk_mul_f32 v[144:145], v[138:139], v[164:165]
	v_pk_fma_f32 v[144:145], v[140:141], v[166:167], v[144:145]
	v_add_f32 v146, v144, v145
	ds_read_b128 v[212:215], v10 offset:15616
	ds_read_b128 v[216:219], v10 offset:15872
	ds_read_b128 v[220:223], v10 offset:16128
	ds_read_b128 v[224:227], v10 offset:16384
	ds_read_b32 v228, v11 offset:15360
	ds_read_b128 v[230:233], v10 offset:16896
	v_add_f32_dpp v146, v146, v146 quad_perm:[1,0,3,2] row_mask:0xf bank_mask:0xf bound_ctrl:1
	v_pk_mul_f32 v[246:247], v[138:139], v[246:247]
	v_pk_fma_f32 v[246:247], v[140:141], v[248:249], v[246:247]
	v_add_f32_dpp v146, v146, v146 quad_perm:[2,3,0,1] row_mask:0xf bank_mask:0xf bound_ctrl:1
	s_waitcnt lgkmcnt(12)
	v_pk_mul_f32 v[176:177], v[176:177], v[184:185] op_sel_hi:[1,0]
	v_add_f32_dpp v146, v146, v146 row_half_mirror row_mask:0xf bank_mask:0xf bound_ctrl:1
	v_pk_mul_f32 v[178:179], v[178:179], v[184:185] op_sel_hi:[1,0]
	v_add_f32 v155, v246, v247
	v_add_f32_dpp v146, v146, v146 row_mirror row_mask:0xf bank_mask:0xf bound_ctrl:1
	v_pk_fma_f32 v[176:177], v[146:147], v[168:169], v[176:177] op_sel_hi:[0,1,1] neg_lo:[1,0,0] neg_hi:[1,0,0]
	v_pk_fma_f32 v[178:179], v[146:147], v[170:171], v[178:179] op_sel_hi:[0,1,1] neg_lo:[1,0,0] neg_hi:[1,0,0]
	v_pk_fma_f32 v[138:139], v[138:139], v[172:173], v[176:177]
	v_pk_fma_f32 v[140:141], v[140:141], v[174:175], v[178:179]
	v_pk_mul_f32 v[144:145], v[138:139], v[186:187]
	v_pk_fma_f32 v[144:145], v[140:141], v[188:189], v[144:145]
	v_add_f32 v146, v144, v145
	ds_read_b128 v[234:237], v10 offset:17152
	ds_read_b128 v[238:241], v10 offset:17408
	ds_read_b128 v[242:245], v10 offset:17664
	ds_read_b128 v[246:249], v10 offset:17920
	ds_read_b32 v250, v11 offset:16896
	ds_read_b128 v[164:167], v10 offset:18432
	v_add_f32_dpp v146, v146, v146 quad_perm:[1,0,3,2] row_mask:0xf bank_mask:0xf bound_ctrl:1
	v_pk_mul_f32 v[180:181], v[138:139], v[180:181]
	v_pk_fma_f32 v[180:181], v[140:141], v[182:183], v[180:181]
	v_add_f32_dpp v146, v146, v146 quad_perm:[2,3,0,1] row_mask:0xf bank_mask:0xf bound_ctrl:1
	s_waitcnt lgkmcnt(12)
	v_pk_mul_f32 v[198:199], v[198:199], v[206:207] op_sel_hi:[1,0]
	v_add_f32_dpp v146, v146, v146 row_half_mirror row_mask:0xf bank_mask:0xf bound_ctrl:1
	v_pk_mul_f32 v[200:201], v[200:201], v[206:207] op_sel_hi:[1,0]
	v_add_f32 v156, v180, v181
	v_add_f32_dpp v146, v146, v146 row_mirror row_mask:0xf bank_mask:0xf bound_ctrl:1
	v_pk_fma_f32 v[198:199], v[146:147], v[190:191], v[198:199] op_sel_hi:[0,1,1] neg_lo:[1,0,0] neg_hi:[1,0,0]
	v_pk_fma_f32 v[200:201], v[146:147], v[192:193], v[200:201] op_sel_hi:[0,1,1] neg_lo:[1,0,0] neg_hi:[1,0,0]
	v_pk_fma_f32 v[138:139], v[138:139], v[194:195], v[198:199]
	v_pk_fma_f32 v[140:141], v[140:141], v[196:197], v[200:201]
	v_pk_mul_f32 v[144:145], v[138:139], v[208:209]
	v_pk_fma_f32 v[144:145], v[140:141], v[210:211], v[144:145]
	v_add_f32 v146, v144, v145
	ds_read_b128 v[168:171], v10 offset:18688
	ds_read_b128 v[172:175], v10 offset:18944
	ds_read_b128 v[176:179], v10 offset:19200
	ds_read_b128 v[180:183], v10 offset:19456
	ds_read_b32 v184, v11 offset:18432
	ds_read_b128 v[186:189], v10 offset:19968
	v_add_f32_dpp v146, v146, v146 quad_perm:[1,0,3,2] row_mask:0xf bank_mask:0xf bound_ctrl:1
	v_pk_mul_f32 v[202:203], v[138:139], v[202:203]
	v_pk_fma_f32 v[202:203], v[140:141], v[204:205], v[202:203]
	v_add_f32_dpp v146, v146, v146 quad_perm:[2,3,0,1] row_mask:0xf bank_mask:0xf bound_ctrl:1
	s_waitcnt lgkmcnt(12)
	v_pk_mul_f32 v[220:221], v[220:221], v[228:229] op_sel_hi:[1,0]
	v_add_f32_dpp v146, v146, v146 row_half_mirror row_mask:0xf bank_mask:0xf bound_ctrl:1
	v_pk_mul_f32 v[222:223], v[222:223], v[228:229] op_sel_hi:[1,0]
	v_add_f32 v157, v202, v203
	v_add_f32_dpp v146, v146, v146 row_mirror row_mask:0xf bank_mask:0xf bound_ctrl:1
	v_pk_fma_f32 v[220:221], v[146:147], v[212:213], v[220:221] op_sel_hi:[0,1,1] neg_lo:[1,0,0] neg_hi:[1,0,0]
	v_pk_fma_f32 v[222:223], v[146:147], v[214:215], v[222:223] op_sel_hi:[0,1,1] neg_lo:[1,0,0] neg_hi:[1,0,0]
	v_pk_fma_f32 v[138:139], v[138:139], v[216:217], v[220:221]
	v_pk_fma_f32 v[140:141], v[140:141], v[218:219], v[222:223]
	v_pk_mul_f32 v[144:145], v[138:139], v[230:231]
	v_pk_fma_f32 v[144:145], v[140:141], v[232:233], v[144:145]
	v_add_f32 v146, v144, v145
	ds_read_b128 v[190:193], v10 offset:20224
	ds_read_b128 v[194:197], v10 offset:20480
	ds_read_b128 v[198:201], v10 offset:20736
	ds_read_b128 v[202:205], v10 offset:20992
	ds_read_b32 v206, v11 offset:19968
	ds_read_b128 v[208:211], v10 offset:21504
	v_add_f32_dpp v146, v146, v146 quad_perm:[1,0,3,2] row_mask:0xf bank_mask:0xf bound_ctrl:1
	v_pk_mul_f32 v[224:225], v[138:139], v[224:225]
	v_pk_fma_f32 v[224:225], v[140:141], v[226:227], v[224:225]
	v_add_f32_dpp v146, v146, v146 quad_perm:[2,3,0,1] row_mask:0xf bank_mask:0xf bound_ctrl:1
	s_waitcnt lgkmcnt(12)
	v_pk_mul_f32 v[242:243], v[242:243], v[250:251] op_sel_hi:[1,0]
	v_add_f32_dpp v146, v146, v146 row_half_mirror row_mask:0xf bank_mask:0xf bound_ctrl:1
	v_pk_mul_f32 v[244:245], v[244:245], v[250:251] op_sel_hi:[1,0]
	v_add_f32 v158, v224, v225
	v_add_f32_dpp v146, v146, v146 row_mirror row_mask:0xf bank_mask:0xf bound_ctrl:1
	v_pk_fma_f32 v[242:243], v[146:147], v[234:235], v[242:243] op_sel_hi:[0,1,1] neg_lo:[1,0,0] neg_hi:[1,0,0]
	v_pk_fma_f32 v[244:245], v[146:147], v[236:237], v[244:245] op_sel_hi:[0,1,1] neg_lo:[1,0,0] neg_hi:[1,0,0]
	v_pk_fma_f32 v[138:139], v[138:139], v[238:239], v[242:243]
	v_pk_fma_f32 v[140:141], v[140:141], v[240:241], v[244:245]
	v_pk_mul_f32 v[144:145], v[138:139], v[164:165]
	v_pk_fma_f32 v[144:145], v[140:141], v[166:167], v[144:145]
	v_add_f32 v146, v144, v145
	ds_read_b128 v[212:215], v10 offset:21760
	ds_read_b128 v[216:219], v10 offset:22016
	ds_read_b128 v[220:223], v10 offset:22272
	ds_read_b128 v[224:227], v10 offset:22528
	ds_read_b32 v228, v11 offset:21504
	ds_read_b128 v[230:233], v10 offset:23040
	v_add_f32_dpp v146, v146, v146 quad_perm:[1,0,3,2] row_mask:0xf bank_mask:0xf bound_ctrl:1
	v_pk_mul_f32 v[246:247], v[138:139], v[246:247]
	v_pk_fma_f32 v[246:247], v[140:141], v[248:249], v[246:247]
	v_add_f32_dpp v146, v146, v146 quad_perm:[2,3,0,1] row_mask:0xf bank_mask:0xf bound_ctrl:1
	s_waitcnt lgkmcnt(12)
	v_pk_mul_f32 v[176:177], v[176:177], v[184:185] op_sel_hi:[1,0]
	v_add_f32_dpp v146, v146, v146 row_half_mirror row_mask:0xf bank_mask:0xf bound_ctrl:1
	v_pk_mul_f32 v[178:179], v[178:179], v[184:185] op_sel_hi:[1,0]
	v_add_f32 v159, v246, v247
	v_add_f32_dpp v146, v146, v146 row_mirror row_mask:0xf bank_mask:0xf bound_ctrl:1
	v_pk_fma_f32 v[176:177], v[146:147], v[168:169], v[176:177] op_sel_hi:[0,1,1] neg_lo:[1,0,0] neg_hi:[1,0,0]
	v_pk_fma_f32 v[178:179], v[146:147], v[170:171], v[178:179] op_sel_hi:[0,1,1] neg_lo:[1,0,0] neg_hi:[1,0,0]
	v_pk_fma_f32 v[138:139], v[138:139], v[172:173], v[176:177]
	v_pk_fma_f32 v[140:141], v[140:141], v[174:175], v[178:179]
	v_pk_mul_f32 v[144:145], v[138:139], v[186:187]
	v_pk_fma_f32 v[144:145], v[140:141], v[188:189], v[144:145]
	v_add_f32 v146, v144, v145
	ds_read_b128 v[234:237], v10 offset:23296
	ds_read_b128 v[238:241], v10 offset:23552
	ds_read_b128 v[242:245], v10 offset:23808
	ds_read_b128 v[246:249], v10 offset:24064
	ds_read_b32 v250, v11 offset:23040
	ds_read_b128 v[164:167], v10 offset:24576
	v_add_f32_dpp v146, v146, v146 quad_perm:[1,0,3,2] row_mask:0xf bank_mask:0xf bound_ctrl:1
	v_pk_mul_f32 v[180:181], v[138:139], v[180:181]
	v_pk_fma_f32 v[180:181], v[140:141], v[182:183], v[180:181]
	v_add_f32_dpp v146, v146, v146 quad_perm:[2,3,0,1] row_mask:0xf bank_mask:0xf bound_ctrl:1
	s_waitcnt lgkmcnt(12)
	v_pk_mul_f32 v[198:199], v[198:199], v[206:207] op_sel_hi:[1,0]
	v_add_f32_dpp v146, v146, v146 row_half_mirror row_mask:0xf bank_mask:0xf bound_ctrl:1
	v_pk_mul_f32 v[200:201], v[200:201], v[206:207] op_sel_hi:[1,0]
	v_add_f32 v160, v180, v181
	v_add_f32_dpp v146, v146, v146 row_mirror row_mask:0xf bank_mask:0xf bound_ctrl:1
	v_pk_fma_f32 v[198:199], v[146:147], v[190:191], v[198:199] op_sel_hi:[0,1,1] neg_lo:[1,0,0] neg_hi:[1,0,0]
	v_pk_fma_f32 v[200:201], v[146:147], v[192:193], v[200:201] op_sel_hi:[0,1,1] neg_lo:[1,0,0] neg_hi:[1,0,0]
	v_pk_fma_f32 v[138:139], v[138:139], v[194:195], v[198:199]
	v_pk_fma_f32 v[140:141], v[140:141], v[196:197], v[200:201]
	v_pk_mul_f32 v[144:145], v[138:139], v[208:209]
	v_pk_fma_f32 v[144:145], v[140:141], v[210:211], v[144:145]
	v_add_f32 v146, v144, v145
	ds_read_b128 v[168:171], v10 offset:24832
	ds_read_b128 v[172:175], v10 offset:25088
	ds_read_b128 v[176:179], v10 offset:25344
	ds_read_b128 v[180:183], v10 offset:25600
	ds_read_b32 v184, v11 offset:24576
	ds_read_b128 v[186:189], v10 offset:26112
	v_add_f32_dpp v146, v146, v146 quad_perm:[1,0,3,2] row_mask:0xf bank_mask:0xf bound_ctrl:1
	v_pk_mul_f32 v[202:203], v[138:139], v[202:203]
	v_pk_fma_f32 v[202:203], v[140:141], v[204:205], v[202:203]
	v_add_f32_dpp v146, v146, v146 quad_perm:[2,3,0,1] row_mask:0xf bank_mask:0xf bound_ctrl:1
	s_waitcnt lgkmcnt(12)
	v_pk_mul_f32 v[220:221], v[220:221], v[228:229] op_sel_hi:[1,0]
	v_add_f32_dpp v146, v146, v146 row_half_mirror row_mask:0xf bank_mask:0xf bound_ctrl:1
	v_pk_mul_f32 v[222:223], v[222:223], v[228:229] op_sel_hi:[1,0]
	v_add_f32 v161, v202, v203
	v_add_f32_dpp v146, v146, v146 row_mirror row_mask:0xf bank_mask:0xf bound_ctrl:1
	v_pk_fma_f32 v[220:221], v[146:147], v[212:213], v[220:221] op_sel_hi:[0,1,1] neg_lo:[1,0,0] neg_hi:[1,0,0]
	v_pk_fma_f32 v[222:223], v[146:147], v[214:215], v[222:223] op_sel_hi:[0,1,1] neg_lo:[1,0,0] neg_hi:[1,0,0]
	v_pk_fma_f32 v[138:139], v[138:139], v[216:217], v[220:221]
	v_pk_fma_f32 v[140:141], v[140:141], v[218:219], v[222:223]
	v_pk_mul_f32 v[144:145], v[138:139], v[230:231]
	v_pk_fma_f32 v[144:145], v[140:141], v[232:233], v[144:145]
	v_add_f32 v146, v144, v145
	ds_read_b128 v[190:193], v10 offset:26368
	ds_read_b128 v[194:197], v10 offset:26624
	ds_read_b128 v[198:201], v10 offset:26880
	ds_read_b128 v[202:205], v10 offset:27136
	ds_read_b32 v206, v11 offset:26112
	ds_read_b128 v[208:211], v10 offset:27648
	v_add_f32_dpp v146, v146, v146 quad_perm:[1,0,3,2] row_mask:0xf bank_mask:0xf bound_ctrl:1
	v_pk_mul_f32 v[224:225], v[138:139], v[224:225]
	v_pk_fma_f32 v[224:225], v[140:141], v[226:227], v[224:225]
	v_add_f32_dpp v146, v146, v146 quad_perm:[2,3,0,1] row_mask:0xf bank_mask:0xf bound_ctrl:1
	s_waitcnt lgkmcnt(12)
	v_pk_mul_f32 v[242:243], v[242:243], v[250:251] op_sel_hi:[1,0]
	v_add_f32_dpp v146, v146, v146 row_half_mirror row_mask:0xf bank_mask:0xf bound_ctrl:1
	v_pk_mul_f32 v[244:245], v[244:245], v[250:251] op_sel_hi:[1,0]
	v_add_f32 v162, v224, v225
	v_add_f32_dpp v146, v146, v146 row_mirror row_mask:0xf bank_mask:0xf bound_ctrl:1
	v_pk_fma_f32 v[242:243], v[146:147], v[234:235], v[242:243] op_sel_hi:[0,1,1] neg_lo:[1,0,0] neg_hi:[1,0,0]
	v_pk_fma_f32 v[244:245], v[146:147], v[236:237], v[244:245] op_sel_hi:[0,1,1] neg_lo:[1,0,0] neg_hi:[1,0,0]
	v_pk_fma_f32 v[138:139], v[138:139], v[238:239], v[242:243]
	v_pk_fma_f32 v[140:141], v[140:141], v[240:241], v[244:245]
	v_pk_mul_f32 v[144:145], v[138:139], v[164:165]
	v_pk_fma_f32 v[144:145], v[140:141], v[166:167], v[144:145]
	v_add_f32 v146, v144, v145
	ds_read_b128 v[212:215], v10 offset:27904
	ds_read_b128 v[216:219], v10 offset:28160
	ds_read_b128 v[220:223], v10 offset:28416
	ds_read_b128 v[224:227], v10 offset:28672
	ds_read_b32 v228, v11 offset:27648
	ds_read_b128 v[230:233], v10 offset:29184
	v_add_f32_dpp v146, v146, v146 quad_perm:[1,0,3,2] row_mask:0xf bank_mask:0xf bound_ctrl:1
	v_pk_mul_f32 v[246:247], v[138:139], v[246:247]
	v_pk_fma_f32 v[246:247], v[140:141], v[248:249], v[246:247]
	v_add_f32_dpp v146, v146, v146 quad_perm:[2,3,0,1] row_mask:0xf bank_mask:0xf bound_ctrl:1
	s_waitcnt lgkmcnt(12)
	v_pk_mul_f32 v[176:177], v[176:177], v[184:185] op_sel_hi:[1,0]
	v_add_f32_dpp v146, v146, v146 row_half_mirror row_mask:0xf bank_mask:0xf bound_ctrl:1
	v_pk_mul_f32 v[178:179], v[178:179], v[184:185] op_sel_hi:[1,0]
	v_add_f32 v163, v246, v247
	v_add_f32_dpp v146, v146, v146 row_mirror row_mask:0xf bank_mask:0xf bound_ctrl:1
	v_pk_fma_f32 v[176:177], v[146:147], v[168:169], v[176:177] op_sel_hi:[0,1,1] neg_lo:[1,0,0] neg_hi:[1,0,0]
	v_pk_fma_f32 v[178:179], v[146:147], v[170:171], v[178:179] op_sel_hi:[0,1,1] neg_lo:[1,0,0] neg_hi:[1,0,0]
	v_pk_fma_f32 v[138:139], v[138:139], v[172:173], v[176:177]
	v_pk_fma_f32 v[140:141], v[140:141], v[174:175], v[178:179]
	v_pk_mul_f32 v[144:145], v[138:139], v[186:187]
	v_pk_fma_f32 v[144:145], v[140:141], v[188:189], v[144:145]
	v_add_f32 v146, v144, v145
	v_add_f32_dpp v102, v148, v148 row_mirror row_mask:0xf bank_mask:0x3 bound_ctrl:1
	v_add_f32_dpp v102, v156, v156 row_mirror row_mask:0xf bank_mask:0xc bound_ctrl:1
	v_add_f32_dpp v103, v149, v149 row_mirror row_mask:0xf bank_mask:0x3 bound_ctrl:1
	v_add_f32_dpp v103, v157, v157 row_mirror row_mask:0xf bank_mask:0xc bound_ctrl:1
	v_add_f32_dpp v104, v150, v150 row_mirror row_mask:0xf bank_mask:0x3 bound_ctrl:1
	v_add_f32_dpp v104, v158, v158 row_mirror row_mask:0xf bank_mask:0xc bound_ctrl:1
	v_add_f32_dpp v105, v151, v151 row_mirror row_mask:0xf bank_mask:0x3 bound_ctrl:1
	v_add_f32_dpp v105, v159, v159 row_mirror row_mask:0xf bank_mask:0xc bound_ctrl:1
	v_add_f32_dpp v106, v152, v152 row_mirror row_mask:0xf bank_mask:0x3 bound_ctrl:1
	v_add_f32_dpp v106, v160, v160 row_mirror row_mask:0xf bank_mask:0xc bound_ctrl:1
	v_add_f32_dpp v107, v153, v153 row_mirror row_mask:0xf bank_mask:0x3 bound_ctrl:1
	v_add_f32_dpp v107, v161, v161 row_mirror row_mask:0xf bank_mask:0xc bound_ctrl:1
	v_add_f32_dpp v108, v154, v154 row_mirror row_mask:0xf bank_mask:0x3 bound_ctrl:1
	v_add_f32_dpp v108, v162, v162 row_mirror row_mask:0xf bank_mask:0xc bound_ctrl:1
	v_add_f32_dpp v109, v155, v155 row_mirror row_mask:0xf bank_mask:0x3 bound_ctrl:1
	v_add_f32_dpp v109, v163, v163 row_mirror row_mask:0xf bank_mask:0xc bound_ctrl:1
	v_add_f32_dpp v110, v102, v102 row_half_mirror row_mask:0xf bank_mask:0x5 bound_ctrl:1
	v_add_f32_dpp v110, v106, v106 row_half_mirror row_mask:0xf bank_mask:0xa bound_ctrl:1
	v_add_f32_dpp v111, v103, v103 row_half_mirror row_mask:0xf bank_mask:0x5 bound_ctrl:1
	v_add_f32_dpp v111, v107, v107 row_half_mirror row_mask:0xf bank_mask:0xa bound_ctrl:1
	v_add_f32_dpp v112, v104, v104 row_half_mirror row_mask:0xf bank_mask:0x5 bound_ctrl:1
	v_add_f32_dpp v112, v108, v108 row_half_mirror row_mask:0xf bank_mask:0xa bound_ctrl:1
	v_add_f32_dpp v113, v105, v105 row_half_mirror row_mask:0xf bank_mask:0x5 bound_ctrl:1
	v_add_f32_dpp v113, v109, v109 row_half_mirror row_mask:0xf bank_mask:0xa bound_ctrl:1
	s_mov_b32 vcc_lo, 0xcccccccc
	s_mov_b32 vcc_hi, 0xcccccccc
	v_cndmask_b32 v116, v112, v110, vcc
	v_cndmask_b32 v117, v113, v111, vcc
	v_cndmask_b32 v114, v110, v112, vcc
	v_cndmask_b32 v115, v111, v113, vcc
	v_add_f32_dpp v114, v116, v114 quad_perm:[2,3,0,1] row_mask:0xf bank_mask:0xf bound_ctrl:1
	v_add_f32_dpp v115, v117, v115 quad_perm:[2,3,0,1] row_mask:0xf bank_mask:0xf bound_ctrl:1
	s_mov_b32 vcc_lo, 0xaaaaaaaa
	s_mov_b32 vcc_hi, 0xaaaaaaaa
	v_cndmask_b32 v116, v115, v114, vcc
	v_cndmask_b32 v117, v114, v115, vcc
	s_nop 0
	v_add_f32_dpp v18, v116, v117 quad_perm:[1,0,3,2] row_mask:0xf bank_mask:0xf bound_ctrl:1
	ds_read_b128 v[234:237], v10 offset:29440
	ds_read_b128 v[238:241], v10 offset:29696
	ds_read_b128 v[242:245], v10 offset:29952
	ds_read_b128 v[246:249], v10 offset:30208
	ds_read_b32 v250, v11 offset:29184
	ds_read_b128 v[164:167], v10 offset:30720
	v_add_f32_dpp v146, v146, v146 quad_perm:[1,0,3,2] row_mask:0xf bank_mask:0xf bound_ctrl:1
	v_pk_mul_f32 v[180:181], v[138:139], v[180:181]
	v_pk_fma_f32 v[180:181], v[140:141], v[182:183], v[180:181]
	v_add_f32_dpp v146, v146, v146 quad_perm:[2,3,0,1] row_mask:0xf bank_mask:0xf bound_ctrl:1
	s_waitcnt lgkmcnt(12)
	v_pk_mul_f32 v[198:199], v[198:199], v[206:207] op_sel_hi:[1,0]
	v_add_f32_dpp v146, v146, v146 row_half_mirror row_mask:0xf bank_mask:0xf bound_ctrl:1
	v_pk_mul_f32 v[200:201], v[200:201], v[206:207] op_sel_hi:[1,0]
	v_add_f32 v148, v180, v181
	v_add_f32_dpp v146, v146, v146 row_mirror row_mask:0xf bank_mask:0xf bound_ctrl:1
	v_pk_fma_f32 v[198:199], v[146:147], v[190:191], v[198:199] op_sel_hi:[0,1,1] neg_lo:[1,0,0] neg_hi:[1,0,0]
	v_pk_fma_f32 v[200:201], v[146:147], v[192:193], v[200:201] op_sel_hi:[0,1,1] neg_lo:[1,0,0] neg_hi:[1,0,0]
	v_pk_fma_f32 v[138:139], v[138:139], v[194:195], v[198:199]
	v_pk_fma_f32 v[140:141], v[140:141], v[196:197], v[200:201]
	v_pk_mul_f32 v[144:145], v[138:139], v[208:209]
	v_pk_fma_f32 v[144:145], v[140:141], v[210:211], v[144:145]
	v_add_f32 v146, v144, v145
	ds_read_b128 v[168:171], v10 offset:30976
	ds_read_b128 v[172:175], v10 offset:31232
	ds_read_b128 v[176:179], v10 offset:31488
	ds_read_b128 v[180:183], v10 offset:31744
	ds_read_b32 v184, v11 offset:30720
	ds_read_b128 v[186:189], v10 offset:32256
	v_add_f32_dpp v146, v146, v146 quad_perm:[1,0,3,2] row_mask:0xf bank_mask:0xf bound_ctrl:1
	v_pk_mul_f32 v[202:203], v[138:139], v[202:203]
	v_pk_fma_f32 v[202:203], v[140:141], v[204:205], v[202:203]
	v_add_f32_dpp v146, v146, v146 quad_perm:[2,3,0,1] row_mask:0xf bank_mask:0xf bound_ctrl:1
	s_waitcnt lgkmcnt(12)
	v_pk_mul_f32 v[220:221], v[220:221], v[228:229] op_sel_hi:[1,0]
	v_add_f32_dpp v146, v146, v146 row_half_mirror row_mask:0xf bank_mask:0xf bound_ctrl:1
	v_pk_mul_f32 v[222:223], v[222:223], v[228:229] op_sel_hi:[1,0]
	v_add_f32 v149, v202, v203
	v_add_f32_dpp v146, v146, v146 row_mirror row_mask:0xf bank_mask:0xf bound_ctrl:1
	v_pk_fma_f32 v[220:221], v[146:147], v[212:213], v[220:221] op_sel_hi:[0,1,1] neg_lo:[1,0,0] neg_hi:[1,0,0]
	v_pk_fma_f32 v[222:223], v[146:147], v[214:215], v[222:223] op_sel_hi:[0,1,1] neg_lo:[1,0,0] neg_hi:[1,0,0]
	v_pk_fma_f32 v[138:139], v[138:139], v[216:217], v[220:221]
	v_pk_fma_f32 v[140:141], v[140:141], v[218:219], v[222:223]
	v_pk_mul_f32 v[144:145], v[138:139], v[230:231]
	v_pk_fma_f32 v[144:145], v[140:141], v[232:233], v[144:145]
	v_add_f32 v146, v144, v145
	ds_read_b128 v[190:193], v10 offset:32512
	ds_read_b128 v[194:197], v10 offset:32768
	ds_read_b128 v[198:201], v10 offset:33024
	ds_read_b128 v[202:205], v10 offset:33280
	ds_read_b32 v206, v11 offset:32256
	ds_read_b128 v[208:211], v10 offset:33792
	v_add_f32_dpp v146, v146, v146 quad_perm:[1,0,3,2] row_mask:0xf bank_mask:0xf bound_ctrl:1
	v_pk_mul_f32 v[224:225], v[138:139], v[224:225]
	v_pk_fma_f32 v[224:225], v[140:141], v[226:227], v[224:225]
	v_add_f32_dpp v146, v146, v146 quad_perm:[2,3,0,1] row_mask:0xf bank_mask:0xf bound_ctrl:1
	s_waitcnt lgkmcnt(12)
	v_pk_mul_f32 v[242:243], v[242:243], v[250:251] op_sel_hi:[1,0]
	v_add_f32_dpp v146, v146, v146 row_half_mirror row_mask:0xf bank_mask:0xf bound_ctrl:1
	v_pk_mul_f32 v[244:245], v[244:245], v[250:251] op_sel_hi:[1,0]
	v_add_f32 v150, v224, v225
	v_add_f32_dpp v146, v146, v146 row_mirror row_mask:0xf bank_mask:0xf bound_ctrl:1
	v_pk_fma_f32 v[242:243], v[146:147], v[234:235], v[242:243] op_sel_hi:[0,1,1] neg_lo:[1,0,0] neg_hi:[1,0,0]
	v_pk_fma_f32 v[244:245], v[146:147], v[236:237], v[244:245] op_sel_hi:[0,1,1] neg_lo:[1,0,0] neg_hi:[1,0,0]
	v_pk_fma_f32 v[138:139], v[138:139], v[238:239], v[242:243]
	v_pk_fma_f32 v[140:141], v[140:141], v[240:241], v[244:245]
	v_pk_mul_f32 v[144:145], v[138:139], v[164:165]
	v_pk_fma_f32 v[144:145], v[140:141], v[166:167], v[144:145]
	v_add_f32 v146, v144, v145
	ds_read_b128 v[212:215], v10 offset:34048
	ds_read_b128 v[216:219], v10 offset:34304
	ds_read_b128 v[220:223], v10 offset:34560
	ds_read_b128 v[224:227], v10 offset:34816
	ds_read_b32 v228, v11 offset:33792
	ds_read_b128 v[230:233], v10 offset:35328
	v_add_f32_dpp v146, v146, v146 quad_perm:[1,0,3,2] row_mask:0xf bank_mask:0xf bound_ctrl:1
	v_pk_mul_f32 v[246:247], v[138:139], v[246:247]
	v_pk_fma_f32 v[246:247], v[140:141], v[248:249], v[246:247]
	v_add_f32_dpp v146, v146, v146 quad_perm:[2,3,0,1] row_mask:0xf bank_mask:0xf bound_ctrl:1
	s_waitcnt lgkmcnt(12)
	v_pk_mul_f32 v[176:177], v[176:177], v[184:185] op_sel_hi:[1,0]
	v_add_f32_dpp v146, v146, v146 row_half_mirror row_mask:0xf bank_mask:0xf bound_ctrl:1
	v_pk_mul_f32 v[178:179], v[178:179], v[184:185] op_sel_hi:[1,0]
	v_add_f32 v151, v246, v247
	v_add_f32_dpp v146, v146, v146 row_mirror row_mask:0xf bank_mask:0xf bound_ctrl:1
	v_pk_fma_f32 v[176:177], v[146:147], v[168:169], v[176:177] op_sel_hi:[0,1,1] neg_lo:[1,0,0] neg_hi:[1,0,0]
	v_pk_fma_f32 v[178:179], v[146:147], v[170:171], v[178:179] op_sel_hi:[0,1,1] neg_lo:[1,0,0] neg_hi:[1,0,0]
	v_pk_fma_f32 v[138:139], v[138:139], v[172:173], v[176:177]
	v_pk_fma_f32 v[140:141], v[140:141], v[174:175], v[178:179]
	v_pk_mul_f32 v[144:145], v[138:139], v[186:187]
	v_pk_fma_f32 v[144:145], v[140:141], v[188:189], v[144:145]
	v_add_f32 v146, v144, v145
	ds_read_b128 v[234:237], v10 offset:35584
	ds_read_b128 v[238:241], v10 offset:35840
	ds_read_b128 v[242:245], v10 offset:36096
	ds_read_b128 v[246:249], v10 offset:36352
	ds_read_b32 v250, v11 offset:35328
	ds_read_b128 v[164:167], v10 offset:36864
	v_add_f32_dpp v146, v146, v146 quad_perm:[1,0,3,2] row_mask:0xf bank_mask:0xf bound_ctrl:1
	v_pk_mul_f32 v[180:181], v[138:139], v[180:181]
	v_pk_fma_f32 v[180:181], v[140:141], v[182:183], v[180:181]
	v_add_f32_dpp v146, v146, v146 quad_perm:[2,3,0,1] row_mask:0xf bank_mask:0xf bound_ctrl:1
	s_waitcnt lgkmcnt(12)
	v_pk_mul_f32 v[198:199], v[198:199], v[206:207] op_sel_hi:[1,0]
	v_add_f32_dpp v146, v146, v146 row_half_mirror row_mask:0xf bank_mask:0xf bound_ctrl:1
	v_pk_mul_f32 v[200:201], v[200:201], v[206:207] op_sel_hi:[1,0]
	v_add_f32 v152, v180, v181
	v_add_f32_dpp v146, v146, v146 row_mirror row_mask:0xf bank_mask:0xf bound_ctrl:1
	v_pk_fma_f32 v[198:199], v[146:147], v[190:191], v[198:199] op_sel_hi:[0,1,1] neg_lo:[1,0,0] neg_hi:[1,0,0]
	v_pk_fma_f32 v[200:201], v[146:147], v[192:193], v[200:201] op_sel_hi:[0,1,1] neg_lo:[1,0,0] neg_hi:[1,0,0]
	v_pk_fma_f32 v[138:139], v[138:139], v[194:195], v[198:199]
	v_pk_fma_f32 v[140:141], v[140:141], v[196:197], v[200:201]
	v_pk_mul_f32 v[144:145], v[138:139], v[208:209]
	v_pk_fma_f32 v[144:145], v[140:141], v[210:211], v[144:145]
	v_add_f32 v146, v144, v145
	ds_read_b128 v[168:171], v10 offset:37120
	ds_read_b128 v[172:175], v10 offset:37376
	ds_read_b128 v[176:179], v10 offset:37632
	ds_read_b128 v[180:183], v10 offset:37888
	ds_read_b32 v184, v11 offset:36864
	ds_read_b128 v[186:189], v10 offset:38400
	v_add_f32_dpp v146, v146, v146 quad_perm:[1,0,3,2] row_mask:0xf bank_mask:0xf bound_ctrl:1
	v_pk_mul_f32 v[202:203], v[138:139], v[202:203]
	v_pk_fma_f32 v[202:203], v[140:141], v[204:205], v[202:203]
	v_add_f32_dpp v146, v146, v146 quad_perm:[2,3,0,1] row_mask:0xf bank_mask:0xf bound_ctrl:1
	s_waitcnt lgkmcnt(12)
	v_pk_mul_f32 v[220:221], v[220:221], v[228:229] op_sel_hi:[1,0]
	v_add_f32_dpp v146, v146, v146 row_half_mirror row_mask:0xf bank_mask:0xf bound_ctrl:1
	v_pk_mul_f32 v[222:223], v[222:223], v[228:229] op_sel_hi:[1,0]
	v_add_f32 v153, v202, v203
	v_add_f32_dpp v146, v146, v146 row_mirror row_mask:0xf bank_mask:0xf bound_ctrl:1
	v_pk_fma_f32 v[220:221], v[146:147], v[212:213], v[220:221] op_sel_hi:[0,1,1] neg_lo:[1,0,0] neg_hi:[1,0,0]
	v_pk_fma_f32 v[222:223], v[146:147], v[214:215], v[222:223] op_sel_hi:[0,1,1] neg_lo:[1,0,0] neg_hi:[1,0,0]
	v_pk_fma_f32 v[138:139], v[138:139], v[216:217], v[220:221]
	v_pk_fma_f32 v[140:141], v[140:141], v[218:219], v[222:223]
	v_pk_mul_f32 v[144:145], v[138:139], v[230:231]
	v_pk_fma_f32 v[144:145], v[140:141], v[232:233], v[144:145]
	v_add_f32 v146, v144, v145
	ds_read_b128 v[190:193], v10 offset:38656
	ds_read_b128 v[194:197], v10 offset:38912
	ds_read_b128 v[198:201], v10 offset:39168
	ds_read_b128 v[202:205], v10 offset:39424
	ds_read_b32 v206, v11 offset:38400
	ds_read_b128 v[208:211], v10 offset:39936
	v_add_f32_dpp v146, v146, v146 quad_perm:[1,0,3,2] row_mask:0xf bank_mask:0xf bound_ctrl:1
	v_pk_mul_f32 v[224:225], v[138:139], v[224:225]
	v_pk_fma_f32 v[224:225], v[140:141], v[226:227], v[224:225]
	v_add_f32_dpp v146, v146, v146 quad_perm:[2,3,0,1] row_mask:0xf bank_mask:0xf bound_ctrl:1
	s_waitcnt lgkmcnt(12)
	v_pk_mul_f32 v[242:243], v[242:243], v[250:251] op_sel_hi:[1,0]
	v_add_f32_dpp v146, v146, v146 row_half_mirror row_mask:0xf bank_mask:0xf bound_ctrl:1
	v_pk_mul_f32 v[244:245], v[244:245], v[250:251] op_sel_hi:[1,0]
	v_add_f32 v154, v224, v225
	v_add_f32_dpp v146, v146, v146 row_mirror row_mask:0xf bank_mask:0xf bound_ctrl:1
	v_pk_fma_f32 v[242:243], v[146:147], v[234:235], v[242:243] op_sel_hi:[0,1,1] neg_lo:[1,0,0] neg_hi:[1,0,0]
	v_pk_fma_f32 v[244:245], v[146:147], v[236:237], v[244:245] op_sel_hi:[0,1,1] neg_lo:[1,0,0] neg_hi:[1,0,0]
	v_pk_fma_f32 v[138:139], v[138:139], v[238:239], v[242:243]
	v_pk_fma_f32 v[140:141], v[140:141], v[240:241], v[244:245]
	v_pk_mul_f32 v[144:145], v[138:139], v[164:165]
	v_pk_fma_f32 v[144:145], v[140:141], v[166:167], v[144:145]
	v_add_f32 v146, v144, v145
	ds_read_b128 v[212:215], v10 offset:40192
	ds_read_b128 v[216:219], v10 offset:40448
	ds_read_b128 v[220:223], v10 offset:40704
	ds_read_b128 v[224:227], v10 offset:40960
	ds_read_b32 v228, v11 offset:39936
	ds_read_b128 v[230:233], v10 offset:41472
	v_add_f32_dpp v146, v146, v146 quad_perm:[1,0,3,2] row_mask:0xf bank_mask:0xf bound_ctrl:1
	v_pk_mul_f32 v[246:247], v[138:139], v[246:247]
	v_pk_fma_f32 v[246:247], v[140:141], v[248:249], v[246:247]
	v_add_f32_dpp v146, v146, v146 quad_perm:[2,3,0,1] row_mask:0xf bank_mask:0xf bound_ctrl:1
	s_waitcnt lgkmcnt(12)
	v_pk_mul_f32 v[176:177], v[176:177], v[184:185] op_sel_hi:[1,0]
	v_add_f32_dpp v146, v146, v146 row_half_mirror row_mask:0xf bank_mask:0xf bound_ctrl:1
	v_pk_mul_f32 v[178:179], v[178:179], v[184:185] op_sel_hi:[1,0]
	v_add_f32 v155, v246, v247
	v_add_f32_dpp v146, v146, v146 row_mirror row_mask:0xf bank_mask:0xf bound_ctrl:1
	v_pk_fma_f32 v[176:177], v[146:147], v[168:169], v[176:177] op_sel_hi:[0,1,1] neg_lo:[1,0,0] neg_hi:[1,0,0]
	v_pk_fma_f32 v[178:179], v[146:147], v[170:171], v[178:179] op_sel_hi:[0,1,1] neg_lo:[1,0,0] neg_hi:[1,0,0]
	v_pk_fma_f32 v[138:139], v[138:139], v[172:173], v[176:177]
	v_pk_fma_f32 v[140:141], v[140:141], v[174:175], v[178:179]
	v_pk_mul_f32 v[144:145], v[138:139], v[186:187]
	v_pk_fma_f32 v[144:145], v[140:141], v[188:189], v[144:145]
	v_add_f32 v146, v144, v145
	ds_read_b128 v[234:237], v10 offset:41728
	ds_read_b128 v[238:241], v10 offset:41984
	ds_read_b128 v[242:245], v10 offset:42240
	ds_read_b128 v[246:249], v10 offset:42496
	ds_read_b32 v250, v11 offset:41472
	ds_read_b128 v[164:167], v10 offset:43008
	v_add_f32_dpp v146, v146, v146 quad_perm:[1,0,3,2] row_mask:0xf bank_mask:0xf bound_ctrl:1
	v_pk_mul_f32 v[180:181], v[138:139], v[180:181]
	v_pk_fma_f32 v[180:181], v[140:141], v[182:183], v[180:181]
	v_add_f32_dpp v146, v146, v146 quad_perm:[2,3,0,1] row_mask:0xf bank_mask:0xf bound_ctrl:1
	s_waitcnt lgkmcnt(12)
	v_pk_mul_f32 v[198:199], v[198:199], v[206:207] op_sel_hi:[1,0]
	v_add_f32_dpp v146, v146, v146 row_half_mirror row_mask:0xf bank_mask:0xf bound_ctrl:1
	v_pk_mul_f32 v[200:201], v[200:201], v[206:207] op_sel_hi:[1,0]
	v_add_f32 v156, v180, v181
	v_add_f32_dpp v146, v146, v146 row_mirror row_mask:0xf bank_mask:0xf bound_ctrl:1
	v_pk_fma_f32 v[198:199], v[146:147], v[190:191], v[198:199] op_sel_hi:[0,1,1] neg_lo:[1,0,0] neg_hi:[1,0,0]
	v_pk_fma_f32 v[200:201], v[146:147], v[192:193], v[200:201] op_sel_hi:[0,1,1] neg_lo:[1,0,0] neg_hi:[1,0,0]
	v_pk_fma_f32 v[138:139], v[138:139], v[194:195], v[198:199]
	v_pk_fma_f32 v[140:141], v[140:141], v[196:197], v[200:201]
	v_pk_mul_f32 v[144:145], v[138:139], v[208:209]
	v_pk_fma_f32 v[144:145], v[140:141], v[210:211], v[144:145]
	v_add_f32 v146, v144, v145
	ds_read_b128 v[168:171], v10 offset:43264
	ds_read_b128 v[172:175], v10 offset:43520
	ds_read_b128 v[176:179], v10 offset:43776
	ds_read_b128 v[180:183], v10 offset:44032
	ds_read_b32 v184, v11 offset:43008
	ds_read_b128 v[186:189], v10 offset:44544
	v_add_f32_dpp v146, v146, v146 quad_perm:[1,0,3,2] row_mask:0xf bank_mask:0xf bound_ctrl:1
	v_pk_mul_f32 v[202:203], v[138:139], v[202:203]
	v_pk_fma_f32 v[202:203], v[140:141], v[204:205], v[202:203]
	v_add_f32_dpp v146, v146, v146 quad_perm:[2,3,0,1] row_mask:0xf bank_mask:0xf bound_ctrl:1
	s_waitcnt lgkmcnt(12)
	v_pk_mul_f32 v[220:221], v[220:221], v[228:229] op_sel_hi:[1,0]
	v_add_f32_dpp v146, v146, v146 row_half_mirror row_mask:0xf bank_mask:0xf bound_ctrl:1
	v_pk_mul_f32 v[222:223], v[222:223], v[228:229] op_sel_hi:[1,0]
	v_add_f32 v157, v202, v203
	v_add_f32_dpp v146, v146, v146 row_mirror row_mask:0xf bank_mask:0xf bound_ctrl:1
	v_pk_fma_f32 v[220:221], v[146:147], v[212:213], v[220:221] op_sel_hi:[0,1,1] neg_lo:[1,0,0] neg_hi:[1,0,0]
	v_pk_fma_f32 v[222:223], v[146:147], v[214:215], v[222:223] op_sel_hi:[0,1,1] neg_lo:[1,0,0] neg_hi:[1,0,0]
	v_pk_fma_f32 v[138:139], v[138:139], v[216:217], v[220:221]
	v_pk_fma_f32 v[140:141], v[140:141], v[218:219], v[222:223]
	v_pk_mul_f32 v[144:145], v[138:139], v[230:231]
	v_pk_fma_f32 v[144:145], v[140:141], v[232:233], v[144:145]
	v_add_f32 v146, v144, v145
	ds_read_b128 v[190:193], v10 offset:44800
	ds_read_b128 v[194:197], v10 offset:45056
	ds_read_b128 v[198:201], v10 offset:45312
	ds_read_b128 v[202:205], v10 offset:45568
	ds_read_b32 v206, v11 offset:44544
	ds_read_b128 v[208:211], v10 offset:46080
	v_add_f32_dpp v146, v146, v146 quad_perm:[1,0,3,2] row_mask:0xf bank_mask:0xf bound_ctrl:1
	v_pk_mul_f32 v[224:225], v[138:139], v[224:225]
	v_pk_fma_f32 v[224:225], v[140:141], v[226:227], v[224:225]
	v_add_f32_dpp v146, v146, v146 quad_perm:[2,3,0,1] row_mask:0xf bank_mask:0xf bound_ctrl:1
	s_waitcnt lgkmcnt(12)
	v_pk_mul_f32 v[242:243], v[242:243], v[250:251] op_sel_hi:[1,0]
	v_add_f32_dpp v146, v146, v146 row_half_mirror row_mask:0xf bank_mask:0xf bound_ctrl:1
	v_pk_mul_f32 v[244:245], v[244:245], v[250:251] op_sel_hi:[1,0]
	v_add_f32 v158, v224, v225
	v_add_f32_dpp v146, v146, v146 row_mirror row_mask:0xf bank_mask:0xf bound_ctrl:1
	v_pk_fma_f32 v[242:243], v[146:147], v[234:235], v[242:243] op_sel_hi:[0,1,1] neg_lo:[1,0,0] neg_hi:[1,0,0]
	v_pk_fma_f32 v[244:245], v[146:147], v[236:237], v[244:245] op_sel_hi:[0,1,1] neg_lo:[1,0,0] neg_hi:[1,0,0]
	v_pk_fma_f32 v[138:139], v[138:139], v[238:239], v[242:243]
	v_pk_fma_f32 v[140:141], v[140:141], v[240:241], v[244:245]
	v_pk_mul_f32 v[144:145], v[138:139], v[164:165]
	v_pk_fma_f32 v[144:145], v[140:141], v[166:167], v[144:145]
	v_add_f32 v146, v144, v145
	ds_read_b128 v[212:215], v10 offset:46336
	ds_read_b128 v[216:219], v10 offset:46592
	ds_read_b128 v[220:223], v10 offset:46848
	ds_read_b128 v[224:227], v10 offset:47104
	ds_read_b32 v228, v11 offset:46080
	ds_read_b128 v[230:233], v10 offset:47616
	v_add_f32_dpp v146, v146, v146 quad_perm:[1,0,3,2] row_mask:0xf bank_mask:0xf bound_ctrl:1
	v_pk_mul_f32 v[246:247], v[138:139], v[246:247]
	v_pk_fma_f32 v[246:247], v[140:141], v[248:249], v[246:247]
	v_add_f32_dpp v146, v146, v146 quad_perm:[2,3,0,1] row_mask:0xf bank_mask:0xf bound_ctrl:1
	s_waitcnt lgkmcnt(12)
	v_pk_mul_f32 v[176:177], v[176:177], v[184:185] op_sel_hi:[1,0]
	v_add_f32_dpp v146, v146, v146 row_half_mirror row_mask:0xf bank_mask:0xf bound_ctrl:1
	v_pk_mul_f32 v[178:179], v[178:179], v[184:185] op_sel_hi:[1,0]
	v_add_f32 v159, v246, v247
	v_add_f32_dpp v146, v146, v146 row_mirror row_mask:0xf bank_mask:0xf bound_ctrl:1
	v_pk_fma_f32 v[176:177], v[146:147], v[168:169], v[176:177] op_sel_hi:[0,1,1] neg_lo:[1,0,0] neg_hi:[1,0,0]
	v_pk_fma_f32 v[178:179], v[146:147], v[170:171], v[178:179] op_sel_hi:[0,1,1] neg_lo:[1,0,0] neg_hi:[1,0,0]
	v_pk_fma_f32 v[138:139], v[138:139], v[172:173], v[176:177]
	v_pk_fma_f32 v[140:141], v[140:141], v[174:175], v[178:179]
	v_pk_mul_f32 v[144:145], v[138:139], v[186:187]
	v_pk_fma_f32 v[144:145], v[140:141], v[188:189], v[144:145]
	v_add_f32 v146, v144, v145
	ds_read_b128 v[234:237], v10 offset:47872
	ds_read_b128 v[238:241], v10 offset:48128
	ds_read_b128 v[242:245], v10 offset:48384
	ds_read_b128 v[246:249], v10 offset:48640
	ds_read_b32 v250, v11 offset:47616
	v_add_f32_dpp v146, v146, v146 quad_perm:[1,0,3,2] row_mask:0xf bank_mask:0xf bound_ctrl:1
	v_pk_mul_f32 v[180:181], v[138:139], v[180:181]
	v_pk_fma_f32 v[180:181], v[140:141], v[182:183], v[180:181]
	v_add_f32_dpp v146, v146, v146 quad_perm:[2,3,0,1] row_mask:0xf bank_mask:0xf bound_ctrl:1
	s_waitcnt lgkmcnt(11)
; #define SCAN_BAR() asm volatile("s_barrier" ::: "memory")
; __device__ __forceinline__ void scan_unit(const Ctx& C0, const float* scn, int T, int quarter, const float* S0, float* Sout, unsigned char* obase, int mode) {
;     ...
;         for (int k = 0; k < nch; ++k) {
;             const unsigned aq = (unsigned)(size_t)(C.lds + (k & 1) * SLOT_B) + 16u * (unsigned)q, av = (unsigned)(size_t)(C.lds + (k & 1) * SLOT_B) + (320u + (unsigned)irow) * 4u;
;             float osel0, osel1;
;             asm volatile(SCAN_CHUNK_ASM : "+v"(S0x), "+v"(S1x), "+v"(S2x), "+v"(S3x), "=&v"(osel0), "=&v"(osel1) : "v"(aq), "v"(av), "v"(q) : SCAN_CHUNK_CLOBBERS, "memory");
;             if (mode == 0) { *(float*)(obase + (size_t)(k * 32 + q) * UPITCH_B + rl * 4) = osel0; *(float*)(obase + (size_t)(k * 32 + 16 + q) * UPITCH_B + rl * 4) = osel1; }
;             SCAN_BAR();
	v_pk_mul_f32 v[198:199], v[198:199], v[206:207] op_sel_hi:[1,0]
	v_add_f32_dpp v146, v146, v146 row_half_mirror row_mask:0xf bank_mask:0xf bound_ctrl:1
	v_pk_mul_f32 v[200:201], v[200:201], v[206:207] op_sel_hi:[1,0]
	v_add_f32 v160, v180, v181
	v_add_f32_dpp v146, v146, v146 row_mirror row_mask:0xf bank_mask:0xf bound_ctrl:1
	v_pk_fma_f32 v[198:199], v[146:147], v[190:191], v[198:199] op_sel_hi:[0,1,1] neg_lo:[1,0,0] neg_hi:[1,0,0]
	v_pk_fma_f32 v[200:201], v[146:147], v[192:193], v[200:201] op_sel_hi:[0,1,1] neg_lo:[1,0,0] neg_hi:[1,0,0]
	v_pk_fma_f32 v[138:139], v[138:139], v[194:195], v[198:199]
	v_pk_fma_f32 v[140:141], v[140:141], v[196:197], v[200:201]
	v_pk_mul_f32 v[144:145], v[138:139], v[208:209]
	v_pk_fma_f32 v[144:145], v[140:141], v[210:211], v[144:145]
	v_add_f32 v146, v144, v145
	s_nop 1
	v_add_f32_dpp v146, v146, v146 quad_perm:[1,0,3,2] row_mask:0xf bank_mask:0xf bound_ctrl:1
	v_pk_mul_f32 v[202:203], v[138:139], v[202:203]
	v_pk_fma_f32 v[202:203], v[140:141], v[204:205], v[202:203]
	v_add_f32_dpp v146, v146, v146 quad_perm:[2,3,0,1] row_mask:0xf bank_mask:0xf bound_ctrl:1
	s_waitcnt lgkmcnt(5)
	v_pk_mul_f32 v[220:221], v[220:221], v[228:229] op_sel_hi:[1,0]
	v_add_f32_dpp v146, v146, v146 row_half_mirror row_mask:0xf bank_mask:0xf bound_ctrl:1
	v_pk_mul_f32 v[222:223], v[222:223], v[228:229] op_sel_hi:[1,0]
	v_add_f32 v161, v202, v203
	v_add_f32_dpp v146, v146, v146 row_mirror row_mask:0xf bank_mask:0xf bound_ctrl:1
	v_pk_fma_f32 v[220:221], v[146:147], v[212:213], v[220:221] op_sel_hi:[0,1,1] neg_lo:[1,0,0] neg_hi:[1,0,0]
	v_pk_fma_f32 v[222:223], v[146:147], v[214:215], v[222:223] op_sel_hi:[0,1,1] neg_lo:[1,0,0] neg_hi:[1,0,0]
	v_pk_fma_f32 v[138:139], v[138:139], v[216:217], v[220:221]
	v_pk_fma_f32 v[140:141], v[140:141], v[218:219], v[222:223]
	v_pk_mul_f32 v[144:145], v[138:139], v[230:231]
	v_pk_fma_f32 v[144:145], v[140:141], v[232:233], v[144:145]
	v_add_f32 v146, v144, v145
	s_nop 1
	v_add_f32_dpp v146, v146, v146 quad_perm:[1,0,3,2] row_mask:0xf bank_mask:0xf bound_ctrl:1
	v_pk_mul_f32 v[224:225], v[138:139], v[224:225]
	v_pk_fma_f32 v[224:225], v[140:141], v[226:227], v[224:225]
	v_add_f32_dpp v146, v146, v146 quad_perm:[2,3,0,1] row_mask:0xf bank_mask:0xf bound_ctrl:1
	s_waitcnt lgkmcnt(0)
	v_pk_mul_f32 v[242:243], v[242:243], v[250:251] op_sel_hi:[1,0]
	v_add_f32_dpp v146, v146, v146 row_half_mirror row_mask:0xf bank_mask:0xf bound_ctrl:1
	v_pk_mul_f32 v[244:245], v[244:245], v[250:251] op_sel_hi:[1,0]
	v_add_f32 v162, v224, v225
	v_add_f32_dpp v146, v146, v146 row_mirror row_mask:0xf bank_mask:0xf bound_ctrl:1
	v_pk_fma_f32 v[242:243], v[146:147], v[234:235], v[242:243] op_sel_hi:[0,1,1] neg_lo:[1,0,0] neg_hi:[1,0,0]
	v_pk_fma_f32 v[244:245], v[146:147], v[236:237], v[244:245] op_sel_hi:[0,1,1] neg_lo:[1,0,0] neg_hi:[1,0,0]
	v_pk_fma_f32 v[138:139], v[138:139], v[238:239], v[242:243]
	v_pk_fma_f32 v[140:141], v[140:141], v[240:241], v[244:245]
	s_barrier
	ds_read_b128 v[164:167], v5 offset:0
	ds_read_b128 v[168:171], v5 offset:256
	ds_read_b128 v[172:175], v5 offset:512
	ds_read_b128 v[176:179], v5 offset:768
	ds_read_b128 v[180:183], v5 offset:1024
	ds_read_b32 v184, v9 offset:0
	ds_read_b128 v[186:189], v5 offset:1536
	ds_read_b128 v[190:193], v5 offset:1792
	ds_read_b128 v[194:197], v5 offset:2048
	ds_read_b128 v[198:201], v5 offset:2304
	ds_read_b128 v[202:205], v5 offset:2560
	ds_read_b32 v206, v9 offset:1536
	ds_read_b128 v[208:211], v5 offset:3072
	v_pk_mul_f32 v[246:247], v[138:139], v[246:247]
	v_pk_fma_f32 v[246:247], v[140:141], v[248:249], v[246:247]
	v_add_f32 v163, v246, v247
	s_nop 0
	v_add_f32_dpp v102, v148, v148 row_mirror row_mask:0xf bank_mask:0x3 bound_ctrl:1
	v_add_f32_dpp v102, v156, v156 row_mirror row_mask:0xf bank_mask:0xc bound_ctrl:1
	v_add_f32_dpp v103, v149, v149 row_mirror row_mask:0xf bank_mask:0x3 bound_ctrl:1
	v_add_f32_dpp v103, v157, v157 row_mirror row_mask:0xf bank_mask:0xc bound_ctrl:1
	v_add_f32_dpp v104, v150, v150 row_mirror row_mask:0xf bank_mask:0x3 bound_ctrl:1
	v_add_f32_dpp v104, v158, v158 row_mirror row_mask:0xf bank_mask:0xc bound_ctrl:1
	v_add_f32_dpp v105, v151, v151 row_mirror row_mask:0xf bank_mask:0x3 bound_ctrl:1
	v_add_f32_dpp v105, v159, v159 row_mirror row_mask:0xf bank_mask:0xc bound_ctrl:1
	v_add_f32_dpp v106, v152, v152 row_mirror row_mask:0xf bank_mask:0x3 bound_ctrl:1
	v_add_f32_dpp v106, v160, v160 row_mirror row_mask:0xf bank_mask:0xc bound_ctrl:1
	v_add_f32_dpp v107, v153, v153 row_mirror row_mask:0xf bank_mask:0x3 bound_ctrl:1
	v_add_f32_dpp v107, v161, v161 row_mirror row_mask:0xf bank_mask:0xc bound_ctrl:1
	v_add_f32_dpp v108, v154, v154 row_mirror row_mask:0xf bank_mask:0x3 bound_ctrl:1
	v_add_f32_dpp v108, v162, v162 row_mirror row_mask:0xf bank_mask:0xc bound_ctrl:1
	v_add_f32_dpp v109, v155, v155 row_mirror row_mask:0xf bank_mask:0x3 bound_ctrl:1
	v_add_f32_dpp v109, v163, v163 row_mirror row_mask:0xf bank_mask:0xc bound_ctrl:1
	v_add_f32_dpp v110, v102, v102 row_half_mirror row_mask:0xf bank_mask:0x5 bound_ctrl:1
	v_add_f32_dpp v110, v106, v106 row_half_mirror row_mask:0xf bank_mask:0xa bound_ctrl:1
	v_add_f32_dpp v111, v103, v103 row_half_mirror row_mask:0xf bank_mask:0x5 bound_ctrl:1
	v_add_f32_dpp v111, v107, v107 row_half_mirror row_mask:0xf bank_mask:0xa bound_ctrl:1
	v_add_f32_dpp v112, v104, v104 row_half_mirror row_mask:0xf bank_mask:0x5 bound_ctrl:1
	v_add_f32_dpp v112, v108, v108 row_half_mirror row_mask:0xf bank_mask:0xa bound_ctrl:1
	v_add_f32_dpp v113, v105, v105 row_half_mirror row_mask:0xf bank_mask:0x5 bound_ctrl:1
	v_add_f32_dpp v113, v109, v109 row_half_mirror row_mask:0xf bank_mask:0xa bound_ctrl:1
	s_mov_b32 vcc_lo, 0xcccccccc
	s_mov_b32 vcc_hi, 0xcccccccc
	v_cndmask_b32 v116, v112, v110, vcc
	v_cndmask_b32 v117, v113, v111, vcc
	v_cndmask_b32 v114, v110, v112, vcc
	v_cndmask_b32 v115, v111, v113, vcc
	v_add_f32_dpp v114, v116, v114 quad_perm:[2,3,0,1] row_mask:0xf bank_mask:0xf bound_ctrl:1
	v_add_f32_dpp v115, v117, v115 quad_perm:[2,3,0,1] row_mask:0xf bank_mask:0xf bound_ctrl:1
	s_mov_b32 vcc_lo, 0xaaaaaaaa
	s_mov_b32 vcc_hi, 0xaaaaaaaa
	v_cndmask_b32 v116, v115, v114, vcc
	v_cndmask_b32 v117, v114, v115, vcc
	s_nop 0
	v_add_f32_dpp v19, v116, v117 quad_perm:[1,0,3,2] row_mask:0xf bank_mask:0xf bound_ctrl:1

; #define SCAN_BAR() asm volatile("s_barrier" ::: "memory")
; __device__ __forceinline__ void scan_unit(const Ctx& C0, const float* scn, int T, int quarter, const float* S0, float* Sout, unsigned char* obase, int mode) {
;     ...
;             if (mode == 0) { *(float*)(obase + (size_t)(k * 32 + q) * UPITCH_B + rl * 4) = osel0; *(float*)(obase + (size_t)(k * 32 + 16 + q) * UPITCH_B + rl * 4) = osel1; }
;             SCAN_BAR();
;         }
;         if (mode == 0) *(f32x4*)(Sout + irow * 64 + 4 * q) = (f32x4){S0x, S1x, S2x, S3x};
	s_addc_u32 s1, s1, 0
	v_add_co_u32_e32 v16, vcc, s8, v14
	s_cmp_lg_u32 s0, 0x5600000
	s_nop 0
	v_addc_co_u32_e32 v17, vcc, 0, v15, vcc
	v_add_co_u32_e32 v14, vcc, 0xfcaa000, v14
	global_store_dword v[16:17], v18, off offset:768
	s_nop 0
	v_addc_co_u32_e32 v15, vcc, 0, v15, vcc
	global_store_dword v[14:15], v19, off offset:768
	s_cbranch_scc1 .LBB0_685
	v_mov_b32_e32 v2, v138
	v_mov_b32_e32 v13, v139
	v_mov_b32_e32 v12, v140
	v_mov_b32_e32 v8, v141
	v_readlane_b32 s0, v255, 46
	s_add_i32 s0, s3, s0
	s_ashr_i32 s1, s0, 31
	s_lshl_b64 s[0:1], s[0:1], 17
	v_readlane_b32 s3, v253, 26
	s_add_u32 s0, s3, s0
	v_readlane_b32 s3, v253, 27
	s_addc_u32 s1, s3, s1
	s_lshl_b32 s2, s2, 14
	s_add_u32 s0, s0, s2
	s_addc_u32 s1, s1, 0
	v_lshlrev_b32_e32 v0, 8, v0
	v_lshl_add_u64 v[6:7], s[0:1], 0, v[0:1]
	v_mov_b32_e32 v5, v1
	v_lshl_add_u64 v[6:7], v[6:7], 0, v[4:5]
	v_mov_b32_e32 v3, v13
	v_mov_b32_e32 v4, v12
	v_mov_b32_e32 v5, v8
	global_store_dwordx4 v[6:7], v[2:5], off
